# phase3 seg-pair balance + gn/LDS read hoist, attn head-loop vmcnt relax
# speedup vs baseline: 1.0009x; 1.0009x over previous
.LBB0_409:
.LBB0_410:
	v_readlane_b32 s0, v254, 10
	s_cmpk_gt_i32 s0, 0x1ff
	v_readlane_b32 s1, v254, 11
	s_cbranch_scc1 .LBB0_427
	v_readlane_b32 s0, v254, 15
	v_readlane_b32 s1, v254, 16
	s_load_dwordx2 s[0:1], s[0:1], 0xa8
	s_add_i32 s54, s91, 0x11c00
	s_add_i32 s55, s91, 0x11800
	s_add_i32 s56, s91, 0x11e00
	v_readlane_b32 s2, v254, 10
	s_and_b32 s3, s2, 7
	s_lshr_b32 s4, s3, 1
	s_sub_i32 s5, 7, s4
	s_bitcmp1_b32 s3, 0
	s_cselect_b32 s4, s5, s4
	s_andn2_b32 s2, s2, 7
	s_or_b32 s2, s2, s4
	s_waitcnt lgkmcnt(0)
	s_add_u32 s38, s0, 0x5660000
	s_addc_u32 s39, s1, 0
	s_add_u32 s40, s0, 0x1c900000
	s_addc_u32 s41, s1, 0
	s_add_u32 s42, s0, 0x1a900000
	s_addc_u32 s43, s1, 0
	s_add_u32 s44, s0, 0x15860000
	v_mbcnt_lo_u32_b32 v0, -1, 0
	s_addc_u32 s45, s1, 0
	s_add_i32 s57, s2, 1
	v_mov_b32_e32 v113, 0
	s_movk_i32 s58, 0x1000
	s_mov_b32 s47, 0
	s_movk_i32 s59, 0x2000
	s_movk_i32 s60, 0x3000
	s_movk_i32 s61, 0x90
	v_mbcnt_hi_u32_b32 v160, -1, v0
	s_movk_i32 s62, 0x2200
	s_mov_b32 s63, 0x96e0000
	s_mov_b32 s64, 0x96e1000
	s_mov_b32 s65, 0xd760000
	s_mov_b32 s66, 0x5660000
	s_mov_b32 s67, 0xd761000
	s_mov_b32 s68, 0x5661000
	s_mov_b32 s69, 0xc2a00000
	v_mov_b32_e32 v161, 0x358637bd
	s_mov_b32 s70, 0x800000
	s_mov_b64 s[48:49], 0x4080000
	s_mov_b32 s71, 0x4081000
	s_mov_b32 s72, 0x4082000
	s_mov_b32 s73, 0x4083000
	s_mov_b32 s74, 0x4084000
	s_mov_b32 s75, 0x4085000
	s_mov_b32 s76, 0x4086000
	s_mov_b32 s77, 0x4087000
	s_mov_b32 s78, 0x4088000
	s_mov_b32 s79, 0x4089000
	s_mov_b32 s80, 0x408a000
	s_mov_b32 s81, 0x408b000
	s_mov_b32 s82, 0x408c000
	s_mov_b32 s83, 0x408d000
	s_mov_b32 s84, 0x408e000
	v_mov_b32_e32 v162, 0x42a00000
	s_mov_b32 s85, s2
	v_readlane_b32 s3, v254, 11
	s_branch .LBB0_413

.LBB0_422:
	s_or_b64 exec, exec, s[36:37]
	s_waitcnt lgkmcnt(0)
	s_barrier
	ds_read_b128 v[0:3], v167
	ds_read_b128 v[4:7], v167 offset:416
	ds_read_b128 v[8:11], v167 offset:448
	ds_read_b128 v[216:219], v167 offset:32
	ds_read_b128 v[12:15], v167 offset:480
	ds_read_b128 v[220:223], v167 offset:64
	ds_read_b128 v[224:227], v167 offset:96
	ds_read_b128 v[228:231], v167 offset:128
	ds_read_b128 v[232:235], v167 offset:160
	ds_read_b128 v[236:239], v167 offset:192
	ds_read_b128 v[240:243], v167 offset:224
	ds_read_b128 v[244:247], v167 offset:256
	v_add_u32_e32 v157, v170, v179
	s_add_u32 s52, s52, 0x4000
	s_waitcnt lgkmcnt(11)
	v_pk_mul_f32 v[48:49], v[108:109], v[0:1]
	ds_read_b128 v[248:251], v167 offset:288
	v_pk_mul_f32 v[50:51], v[114:115], v[2:3]
	v_cvt_pk_bf16_f32 v64, v48, v49
	v_cvt_pk_bf16_f32 v65, v50, v51
	s_waitcnt lgkmcnt(11)
	v_pk_mul_f32 v[4:5], v[144:145], v[4:5]
	s_waitcnt lgkmcnt(9)
	v_pk_mul_f32 v[52:53], v[52:53], v[216:217]
	v_pk_mul_f32 v[54:55], v[54:55], v[218:219]
	ds_read_b128 v[216:219], v167 offset:320
	v_cvt_pk_bf16_f32 v66, v52, v53
	v_cvt_pk_bf16_f32 v67, v54, v55
	v_pk_mul_f32 v[6:7], v[138:139], v[6:7]
	v_pk_mul_f32 v[8:9], v[146:147], v[8:9]
	s_waitcnt lgkmcnt(8)
	v_pk_mul_f32 v[56:57], v[56:57], v[220:221]
	v_pk_mul_f32 v[58:59], v[58:59], v[222:223]
	ds_read_b128 v[220:223], v167 offset:352
	v_pk_mul_f32 v[10:11], v[140:141], v[10:11]
	v_pk_mul_f32 v[12:13], v[148:149], v[12:13]
	v_pk_mul_f32 v[14:15], v[142:143], v[14:15]
	s_addc_u32 s53, s53, 0
	s_waitcnt lgkmcnt(8)
	v_pk_mul_f32 v[60:61], v[60:61], v[224:225]
	v_pk_mul_f32 v[62:63], v[62:63], v[226:227]
	ds_read_b128 v[224:227], v167 offset:384
	ds_read2_b64 v[68:71], v180 offset1:2
	s_cmp_eq_u32 s52, 0x20000
	s_waitcnt lgkmcnt(9)
	v_pk_mul_f32 v[32:33], v[100:101], v[228:229]
	v_pk_mul_f32 v[34:35], v[96:97], v[230:231]
	ds_read2_b64 v[228:231], v180 offset0:4 offset1:6
	v_cvt_pk_bf16_f32 v100, v56, v57
	v_cvt_pk_bf16_f32 v101, v58, v59
	s_waitcnt lgkmcnt(9)
	v_pk_mul_f32 v[36:37], v[110:111], v[232:233]
	v_pk_mul_f32 v[38:39], v[102:103], v[234:235]
	v_cvt_pk_bf16_f32 v102, v60, v61
	v_cvt_pk_bf16_f32 v103, v62, v63
	s_waitcnt lgkmcnt(8)
	v_pk_mul_f32 v[40:41], v[104:105], v[236:237]
	v_pk_mul_f32 v[42:43], v[98:99], v[238:239]
	v_add_u32_e32 v104, 0x2000, v180
	ds_read2_b64 v[232:235], v104 offset0:64 offset1:66
	ds_read2_b64 v[236:239], v104 offset0:68 offset1:70
	s_waitcnt lgkmcnt(9)
	v_pk_mul_f32 v[44:45], v[116:117], v[240:241]
	v_pk_mul_f32 v[46:47], v[106:107], v[242:243]
	ds_read2_b64 v[240:243], v180 offset0:8 offset1:10
	s_waitcnt lgkmcnt(9)
	v_pk_mul_f32 v[16:17], v[122:123], v[244:245]
	v_pk_mul_f32 v[18:19], v[118:119], v[246:247]
	ds_read2_b64 v[244:247], v104 offset0:72 offset1:74
	s_waitcnt lgkmcnt(9)
	v_pk_mul_f32 v[20:21], v[130:131], v[248:249]
	v_pk_mul_f32 v[22:23], v[124:125], v[250:251]
	ds_read2_b64 v[248:251], v180 offset0:12 offset1:14
	s_waitcnt lgkmcnt(9)
	v_pk_mul_f32 v[24:25], v[126:127], v[216:217]
	v_pk_mul_f32 v[26:27], v[120:121], v[218:219]
	ds_read2_b64 v[216:219], v104 offset0:76 offset1:78
	s_waitcnt lgkmcnt(9)
	v_pk_mul_f32 v[28:29], v[132:133], v[220:221]
	v_pk_mul_f32 v[30:31], v[128:129], v[222:223]
	ds_read2_b64 v[220:223], v180 offset0:16 offset1:18
	s_waitcnt lgkmcnt(8)
	v_mfma_f32_32x32x16_bf16 v[80:95], v[64:67], v[68:71], 0
	v_mul_f32_e64 v0, v136, v224
	v_mul_f32_e64 v1, v137, v225
	v_mul_f32_e64 v2, v134, v226
	v_mul_f32_e64 v3, v135, v227
	ds_read2_b64 v[224:227], v104 offset0:80 offset1:82
	s_waitcnt lgkmcnt(7)
	v_mfma_f32_32x32x16_bf16 v[64:79], v[64:67], v[232:235], 0
	ds_read2_b64 v[232:235], v180 offset0:20 offset1:22
	v_mfma_f32_32x32x16_bf16 v[80:95], v[100:103], v[228:231], v[80:95]
	ds_read2_b64 v[228:231], v104 offset0:84 offset1:86
	s_waitcnt lgkmcnt(8)
	v_mfma_f32_32x32x16_bf16 v[64:79], v[100:103], v[236:239], v[64:79]
	ds_read2_b64 v[236:239], v180 offset0:24 offset1:26
	v_cvt_pk_bf16_f32 v96, v32, v33
	v_cvt_pk_bf16_f32 v97, v34, v35
	v_cvt_pk_bf16_f32 v98, v36, v37
	v_cvt_pk_bf16_f32 v99, v38, v39
	s_waitcnt lgkmcnt(8)
	s_nop 0
	v_mfma_f32_32x32x16_bf16 v[80:95], v[96:99], v[240:243], v[80:95]
	ds_read2_b64 v[240:243], v104 offset0:88 offset1:90
	s_waitcnt lgkmcnt(8)
	v_mfma_f32_32x32x16_bf16 v[64:79], v[96:99], v[244:247], v[64:79]
	ds_read2_b64 v[244:247], v180 offset0:28 offset1:30
	v_cvt_pk_bf16_f32 v96, v40, v41
	v_cvt_pk_bf16_f32 v97, v42, v43
	v_cvt_pk_bf16_f32 v98, v44, v45
	v_cvt_pk_bf16_f32 v99, v46, v47
	s_waitcnt lgkmcnt(8)
	s_nop 0
	v_mfma_f32_32x32x16_bf16 v[80:95], v[96:99], v[248:251], v[80:95]
	ds_read2_b64 v[248:251], v104 offset0:92 offset1:94
	ds_read_b128 v[114:117], v157 offset:17408
	s_waitcnt lgkmcnt(9)
	v_mfma_f32_32x32x16_bf16 v[64:79], v[96:99], v[216:219], v[64:79]
	ds_read_b128 v[216:219], v157
	ds_read_b128 v[118:121], v157 offset:32
	ds_read_b128 v[122:125], v157 offset:17440
	v_cvt_pk_bf16_f32 v96, v16, v17
	v_cvt_pk_bf16_f32 v97, v18, v19
	v_cvt_pk_bf16_f32 v98, v20, v21
	v_cvt_pk_bf16_f32 v99, v22, v23
	s_waitcnt lgkmcnt(11)
	s_nop 0
	v_mfma_f32_32x32x16_bf16 v[80:95], v[96:99], v[220:223], v[80:95]
	ds_read_b128 v[220:223], v157 offset:17472
	s_waitcnt lgkmcnt(11)
	v_mfma_f32_32x32x16_bf16 v[64:79], v[96:99], v[224:227], v[64:79]
	ds_read_b128 v[126:129], v157 offset:64
	v_cvt_pk_bf16_f32 v96, v24, v25
	v_cvt_pk_bf16_f32 v97, v26, v27
	v_cvt_pk_bf16_f32 v98, v28, v29
	v_cvt_pk_bf16_f32 v99, v30, v31
	s_waitcnt lgkmcnt(11)
	s_nop 0
	v_mfma_f32_32x32x16_bf16 v[80:95], v[96:99], v[232:235], v[80:95]
	ds_read_b128 v[224:227], v157 offset:17504
	s_waitcnt lgkmcnt(11)
	v_mfma_f32_32x32x16_bf16 v[64:79], v[96:99], v[228:231], v[64:79]
	ds_read_b128 v[130:133], v157 offset:96
	v_cvt_pk_bf16_f32 v96, v0, v1
	v_cvt_pk_bf16_f32 v97, v2, v3
	v_cvt_pk_bf16_f32 v98, v4, v5
	v_cvt_pk_bf16_f32 v99, v6, v7
	s_waitcnt lgkmcnt(11)
	s_nop 0
	v_mfma_f32_32x32x16_bf16 v[80:95], v[96:99], v[236:239], v[80:95]
	ds_read_b128 v[228:231], v157 offset:17536
	s_waitcnt lgkmcnt(11)
	v_mfma_f32_32x32x16_bf16 v[64:79], v[96:99], v[240:243], v[64:79]
	ds_read_b128 v[134:137], v157 offset:128
	v_cvt_pk_bf16_f32 v96, v8, v9
	v_cvt_pk_bf16_f32 v97, v10, v11
	v_cvt_pk_bf16_f32 v98, v12, v13
	v_cvt_pk_bf16_f32 v99, v14, v15
	s_waitcnt lgkmcnt(11)
	s_nop 0
	v_mfma_f32_32x32x16_bf16 v[80:95], v[96:99], v[244:247], v[80:95]
	ds_read_b128 v[232:235], v157 offset:17568
	s_waitcnt lgkmcnt(11)
	v_mfma_f32_32x32x16_bf16 v[64:79], v[96:99], v[248:251], v[64:79]
	ds_read_b128 v[138:141], v157 offset:160
	s_waitcnt lgkmcnt(10)
	v_mfma_f32_32x32x16_bf16 v[96:111], v[114:117], v[216:219], 0
	ds_read_b128 v[216:219], v157 offset:17600
	ds_read_b128 v[142:145], v157 offset:192
	s_waitcnt lgkmcnt(10)
	v_mfma_f32_32x32x16_bf16 v[96:111], v[122:125], v[118:121], v[96:111]
	ds_read_b128 v[236:239], v157 offset:17632
	ds_read_b128 v[146:149], v157 offset:224
	s_waitcnt lgkmcnt(10)
	v_mfma_f32_32x32x16_bf16 v[96:111], v[220:223], v[126:129], v[96:111]
	s_waitcnt lgkmcnt(8)
	v_mfma_f32_32x32x16_bf16 v[96:111], v[224:227], v[130:133], v[96:111]
	s_waitcnt lgkmcnt(6)
	v_mfma_f32_32x32x16_bf16 v[96:111], v[228:231], v[134:137], v[96:111]
	s_waitcnt lgkmcnt(4)
	v_mfma_f32_32x32x16_bf16 v[96:111], v[232:235], v[138:141], v[96:111]
	s_waitcnt lgkmcnt(2)
	v_mfma_f32_32x32x16_bf16 v[96:111], v[216:219], v[142:145], v[96:111]
	s_waitcnt lgkmcnt(0)
	v_mfma_f32_32x32x16_bf16 v[96:111], v[236:239], v[146:149], v[96:111]
	s_nop 11
	v_cndmask_b32_e64 v146, v96, 0, s[34:35]
	v_cndmask_b32_e64 v96, v146, v96, s[30:31]
	v_cndmask_b32_e64 v97, 0, v97, s[30:31]
	v_cndmask_b32_e64 v98, v98, 0, s[28:29]
	v_cndmask_b32_e64 v99, v99, 0, s[26:27]
	v_cndmask_b32_e64 v100, v100, 0, s[24:25]
	v_cndmask_b32_e64 v101, v101, 0, s[22:23]
	v_cvt_pk_bf16_f32 v96, v96, v97
	v_cvt_pk_bf16_f32 v97, v98, v99
	v_cvt_pk_bf16_f32 v98, v100, v101
	v_add_u32_e32 v100, v171, v168
	v_add_u32_e32 v183, 0xd000, v100
	ds_read2_b64 v[146:149], v183 offset1:2
	ds_read2_b64 v[184:187], v183 offset0:4 offset1:6
	ds_read_b128 v[188:191], v157 offset:8704
	ds_read_b128 v[240:243], v157 offset:8736
	ds_read_b128 v[244:247], v157 offset:8768
	ds_read_b128 v[248:251], v157 offset:8800
	v_cndmask_b32_e64 v102, v102, 0, s[20:21]
	v_cndmask_b32_e64 v103, v103, 0, s[18:19]
	v_cvt_pk_bf16_f32 v99, v102, v103
	v_cndmask_b32_e64 v104, v104, 0, s[16:17]
	s_waitcnt lgkmcnt(5)
	v_mfma_f32_32x32x16_bf16 v[80:95], v[146:149], v[96:99], v[80:95]
	v_cndmask_b32_e64 v105, v105, 0, s[14:15]
	v_cndmask_b32_e64 v106, v106, 0, s[12:13]
	v_cndmask_b32_e64 v107, v107, 0, s[10:11]
	v_cndmask_b32_e64 v108, v108, 0, s[8:9]
	v_cndmask_b32_e64 v109, v109, 0, s[6:7]
	v_cndmask_b32_e64 v110, v110, 0, s[4:5]
	v_cndmask_b32_e64 v111, v111, 0, s[2:3]
	v_cvt_pk_bf16_f32 v96, v104, v105
	v_cvt_pk_bf16_f32 v97, v106, v107
	v_cvt_pk_bf16_f32 v98, v108, v109
	v_cvt_pk_bf16_f32 v99, v110, v111
	s_nop 0
	s_waitcnt lgkmcnt(4)
	v_mfma_f32_32x32x16_bf16 v[80:95], v[184:187], v[96:99], v[80:95]
	s_waitcnt lgkmcnt(3)
	v_mfma_f32_32x32x16_bf16 v[96:111], v[114:117], v[188:191], 0
	s_waitcnt lgkmcnt(2)
	v_mfma_f32_32x32x16_bf16 v[96:111], v[122:125], v[240:243], v[96:111]
	s_waitcnt lgkmcnt(1)
	v_mfma_f32_32x32x16_bf16 v[96:111], v[220:223], v[244:247], v[96:111]
	ds_read_b128 v[220:223], v157 offset:8832
	s_waitcnt lgkmcnt(1)
	v_mfma_f32_32x32x16_bf16 v[96:111], v[224:227], v[248:251], v[96:111]
	ds_read_b128 v[224:227], v157 offset:8864
	s_waitcnt lgkmcnt(1)
	v_mfma_f32_32x32x16_bf16 v[96:111], v[228:231], v[220:223], v[96:111]
	ds_read_b128 v[228:231], v157 offset:8896
	s_waitcnt lgkmcnt(1)
	v_mfma_f32_32x32x16_bf16 v[96:111], v[232:235], v[224:227], v[96:111]
	ds_read_b128 v[232:235], v157 offset:8928
	s_waitcnt lgkmcnt(1)
	v_mfma_f32_32x32x16_bf16 v[96:111], v[216:219], v[228:231], v[96:111]
	s_waitcnt lgkmcnt(0)
	v_mfma_f32_32x32x16_bf16 v[96:111], v[236:239], v[232:235], v[96:111]
	ds_read_b128 v[142:145], v157 offset:26144
	ds_read_b128 v[216:219], v157 offset:26112
	ds_read_b128 v[236:239], v157 offset:26176
	s_nop 10
	v_cvt_pk_bf16_f32 v96, v96, v97
	v_cvt_pk_bf16_f32 v97, v98, v99
	v_cvt_pk_bf16_f32 v98, v100, v101
	v_cvt_pk_bf16_f32 v99, v102, v103
	s_nop 1
	v_mfma_f32_32x32x16_bf16 v[64:79], v[146:149], v[96:99], v[64:79]
	v_cvt_pk_bf16_f32 v96, v104, v105
	v_cvt_pk_bf16_f32 v97, v106, v107
	v_cvt_pk_bf16_f32 v98, v108, v109
	v_cvt_pk_bf16_f32 v99, v110, v111
	s_nop 1
	v_mfma_f32_32x32x16_bf16 v[64:79], v[184:187], v[96:99], v[64:79]
	s_waitcnt lgkmcnt(1)
	v_mfma_f32_32x32x16_bf16 v[96:111], v[216:219], v[188:191], 0
	ds_read_b128 v[216:219], v157 offset:26208
	v_mfma_f32_32x32x16_bf16 v[96:111], v[142:145], v[240:243], v[96:111]
	ds_read_b128 v[240:243], v157 offset:26240
	s_waitcnt lgkmcnt(2)
	v_mfma_f32_32x32x16_bf16 v[96:111], v[236:239], v[244:247], v[96:111]
	ds_read_b128 v[236:239], v157 offset:26272
	ds_read_b128 v[244:247], v157 offset:26304
	s_waitcnt lgkmcnt(3)
	v_mfma_f32_32x32x16_bf16 v[96:111], v[216:219], v[248:251], v[96:111]
	ds_read_b128 v[216:219], v157 offset:26336
	ds_read2_b64 v[248:251], v183 offset0:8 offset1:10
	s_waitcnt lgkmcnt(4)
	v_mfma_f32_32x32x16_bf16 v[96:111], v[240:243], v[220:223], v[96:111]
	ds_read2_b64 v[220:223], v183 offset0:12 offset1:14
	s_waitcnt lgkmcnt(4)
	v_mfma_f32_32x32x16_bf16 v[96:111], v[236:239], v[224:227], v[96:111]
	s_waitcnt lgkmcnt(3)
	v_mfma_f32_32x32x16_bf16 v[96:111], v[244:247], v[228:231], v[96:111]
	v_ashrrev_i32_e32 v157, 31, v156
	s_waitcnt lgkmcnt(2)
	v_mfma_f32_32x32x16_bf16 v[96:111], v[216:219], v[232:235], v[96:111]
	s_nop 11
	v_cndmask_b32_e64 v114, v96, 0, s[34:35]
	v_cndmask_b32_e64 v96, v114, v96, s[30:31]
	v_cndmask_b32_e64 v97, 0, v97, s[30:31]
	v_cndmask_b32_e64 v98, v98, 0, s[28:29]
	v_cndmask_b32_e64 v99, v99, 0, s[26:27]
	v_cndmask_b32_e64 v100, v100, 0, s[24:25]
	v_cndmask_b32_e64 v101, v101, 0, s[22:23]
	v_cndmask_b32_e64 v102, v102, 0, s[20:21]
	v_cndmask_b32_e64 v103, v103, 0, s[18:19]
	v_cvt_pk_bf16_f32 v96, v96, v97
	v_cvt_pk_bf16_f32 v97, v98, v99
	v_cvt_pk_bf16_f32 v98, v100, v101
	v_cvt_pk_bf16_f32 v99, v102, v103
	v_cndmask_b32_e64 v104, v104, 0, s[16:17]
	s_waitcnt lgkmcnt(1)
	v_mfma_f32_32x32x16_bf16 v[64:79], v[248:251], v[96:99], v[64:79]
	v_cndmask_b32_e64 v105, v105, 0, s[14:15]
	v_cndmask_b32_e64 v106, v106, 0, s[12:13]
	v_cndmask_b32_e64 v107, v107, 0, s[10:11]
	v_cndmask_b32_e64 v108, v108, 0, s[8:9]
	v_cndmask_b32_e64 v109, v109, 0, s[6:7]
	v_cndmask_b32_e64 v110, v110, 0, s[4:5]
	v_cndmask_b32_e64 v111, v111, 0, s[2:3]
	v_cvt_pk_bf16_f32 v96, v104, v105
	v_cvt_pk_bf16_f32 v97, v106, v107
	v_cvt_pk_bf16_f32 v98, v108, v109
	v_cvt_pk_bf16_f32 v99, v110, v111
	v_add_u32_e32 v108, v171, v169
	ds_read_b128 v[216:219], v108 offset:53248
	ds_read_b128 v[224:227], v108 offset:53280
	ds_read_b128 v[104:107], v108 offset:53312
	ds_read_b128 v[108:111], v108 offset:53344
	ds_read_b128 v[114:117], v181 offset:34816
	ds_read_b128 v[118:121], v181 offset:34848
	ds_read_b128 v[228:231], v181 offset:34880
	ds_read_b128 v[232:235], v181 offset:34912
	ds_read_b128 v[236:239], v181 offset:39424
	ds_read_b128 v[240:243], v181 offset:39456
	ds_read_b128 v[244:247], v181 offset:39488
	s_waitcnt lgkmcnt(11)
	v_mfma_f32_32x32x16_bf16 v[64:79], v[220:223], v[96:99], v[64:79]
	ds_read_b128 v[220:223], v181 offset:39520
	s_waitcnt lgkmcnt(7)
	v_mfma_f32_32x32x16_bf16 v[48:63], v[114:117], v[216:219], v[48:63]
	ds_read_b128 v[248:251], v181 offset:44032
	s_waitcnt lgkmcnt(7)
	v_mfma_f32_32x32x16_bf16 v[48:63], v[118:121], v[224:227], v[48:63]
	s_waitcnt lgkmcnt(6)
	v_mfma_f32_32x32x16_bf16 v[48:63], v[228:231], v[104:107], v[48:63]
	ds_read_b128 v[228:231], v181 offset:44064
	s_waitcnt lgkmcnt(6)
	v_mfma_f32_32x32x16_bf16 v[48:63], v[232:235], v[108:111], v[48:63]
	ds_read_b128 v[232:235], v181 offset:44096
	s_waitcnt lgkmcnt(6)
	v_mfma_f32_32x32x16_bf16 v[32:47], v[236:239], v[216:219], v[32:47]
	ds_read_b128 v[236:239], v181 offset:44128
	s_waitcnt lgkmcnt(6)
	v_mfma_f32_32x32x16_bf16 v[32:47], v[240:243], v[224:227], v[32:47]
	ds_read_b128 v[240:243], v181 offset:48640
	s_waitcnt lgkmcnt(6)
	v_mfma_f32_32x32x16_bf16 v[32:47], v[244:247], v[104:107], v[32:47]
	ds_read_b128 v[244:247], v181 offset:48672
	s_waitcnt lgkmcnt(6)
	v_mfma_f32_32x32x16_bf16 v[32:47], v[220:223], v[108:111], v[32:47]
	ds_read_b128 v[220:223], v181 offset:48704
	s_waitcnt lgkmcnt(6)
	v_mfma_f32_32x32x16_bf16 v[16:31], v[248:251], v[216:219], v[16:31]
	ds_read_b128 v[248:251], v181 offset:48736
	s_waitcnt lgkmcnt(6)
	v_mfma_f32_32x32x16_bf16 v[16:31], v[228:231], v[224:227], v[16:31]
	ds_read_b128 v[228:231], v172
	s_waitcnt lgkmcnt(6)
	v_mfma_f32_32x32x16_bf16 v[16:31], v[232:235], v[104:107], v[16:31]
	ds_read_b128 v[232:235], v172 offset:32
	s_waitcnt lgkmcnt(6)
	v_mfma_f32_32x32x16_bf16 v[16:31], v[236:239], v[108:111], v[16:31]
	ds_read_b128 v[236:239], v172 offset:64
	s_waitcnt lgkmcnt(6)
	v_mfma_f32_32x32x16_bf16 v[0:15], v[240:243], v[216:219], v[0:15]
	ds_read_b128 v[216:219], v172 offset:96
	s_waitcnt lgkmcnt(6)
	v_mfma_f32_32x32x16_bf16 v[0:15], v[244:247], v[224:227], v[0:15]
	s_waitcnt lgkmcnt(5)
	v_mfma_f32_32x32x16_bf16 v[0:15], v[220:223], v[104:107], v[0:15]
	s_waitcnt lgkmcnt(4)
	v_mfma_f32_32x32x16_bf16 v[0:15], v[248:251], v[108:111], v[0:15]
	s_waitcnt lgkmcnt(3)
	v_mul_f32_e64 v108, v48, v228
	v_mul_f32_e64 v109, v49, v229
	v_pk_mul_f32 v[114:115], v[50:51], v[230:231]
	s_waitcnt lgkmcnt(2)
	v_pk_mul_f32 v[52:53], v[52:53], v[232:233]
	v_pk_mul_f32 v[54:55], v[54:55], v[234:235]
	s_waitcnt lgkmcnt(1)
	v_pk_mul_f32 v[56:57], v[56:57], v[236:237]
	v_pk_mul_f32 v[58:59], v[58:59], v[238:239]
	s_waitcnt lgkmcnt(0)
	v_pk_mul_f32 v[60:61], v[60:61], v[216:217]
	v_pk_mul_f32 v[62:63], v[62:63], v[218:219]
	ds_read_b128 v[48:51], v172 offset:128
	ds_read_b128 v[216:219], v172 offset:160
	ds_read_b128 v[220:223], v172 offset:192
	ds_read_b128 v[224:227], v172 offset:224
	s_waitcnt lgkmcnt(3)
	v_pk_mul_f32 v[100:101], v[32:33], v[48:49]
	v_pk_mul_f32 v[96:97], v[34:35], v[50:51]
	s_waitcnt lgkmcnt(2)
	v_pk_mul_f32 v[110:111], v[36:37], v[216:217]
	v_pk_mul_f32 v[102:103], v[38:39], v[218:219]
	s_waitcnt lgkmcnt(1)
	v_pk_mul_f32 v[104:105], v[40:41], v[220:221]
	v_pk_mul_f32 v[98:99], v[42:43], v[222:223]
	s_waitcnt lgkmcnt(0)
	v_pk_mul_f32 v[116:117], v[44:45], v[224:225]
	v_pk_mul_f32 v[106:107], v[46:47], v[226:227]
	ds_read_b128 v[32:35], v172 offset:256
	ds_read_b128 v[216:219], v172 offset:288
	ds_read_b128 v[220:223], v172 offset:320
	ds_read_b128 v[224:227], v172 offset:352
	s_waitcnt lgkmcnt(3)
	v_pk_mul_f32 v[122:123], v[16:17], v[32:33]
	v_pk_mul_f32 v[118:119], v[18:19], v[34:35]
	s_waitcnt lgkmcnt(2)
	v_pk_mul_f32 v[130:131], v[20:21], v[216:217]
	v_pk_mul_f32 v[124:125], v[22:23], v[218:219]
	s_waitcnt lgkmcnt(1)
	v_pk_mul_f32 v[126:127], v[24:25], v[220:221]
	v_pk_mul_f32 v[120:121], v[26:27], v[222:223]
	s_waitcnt lgkmcnt(0)
	v_pk_mul_f32 v[132:133], v[28:29], v[224:225]
	v_pk_mul_f32 v[128:129], v[30:31], v[226:227]
	ds_read_b128 v[16:19], v172 offset:384
	ds_read_b128 v[216:219], v172 offset:416
	ds_read_b128 v[220:223], v172 offset:448
	v_lshlrev_b64 v[30:31], 12, v[156:157]
	s_waitcnt lgkmcnt(2)
	v_pk_mul_f32 v[136:137], v[0:1], v[16:17]
	v_pk_mul_f32 v[134:135], v[2:3], v[18:19]
	s_waitcnt lgkmcnt(1)
	v_pk_mul_f32 v[144:145], v[4:5], v[216:217]
	v_pk_mul_f32 v[138:139], v[6:7], v[218:219]
	s_waitcnt lgkmcnt(0)
	v_pk_mul_f32 v[146:147], v[8:9], v[220:221]
	v_pk_mul_f32 v[140:141], v[10:11], v[222:223]
	ds_read_b128 v[0:3], v172 offset:480
	s_waitcnt lgkmcnt(0)
	s_barrier
	ds_write_b128 v182, v[80:83]
	ds_write_b128 v182, v[84:87] offset:32
	ds_write_b128 v182, v[88:91] offset:64
	ds_write_b128 v182, v[92:95] offset:96
	ds_write_b128 v182, v[64:67] offset:16896
	ds_write_b128 v182, v[68:71] offset:16928
	ds_write_b128 v182, v[72:75] offset:16960
	ds_write_b128 v182, v[76:79] offset:16992
	v_pk_mul_f32 v[148:149], v[12:13], v[0:1]
	v_pk_mul_f32 v[142:143], v[14:15], v[2:3]
	s_waitcnt lgkmcnt(0)
	s_barrier
	ds_read_b128 v[16:19], v173 offset:64
	ds_read_b128 v[12:15], v173 offset:80
	v_lshl_add_u64 v[64:65], v[152:153], 0, v[30:31]
	s_waitcnt lgkmcnt(1)
	v_pk_mul_f32 v[4:5], v[16:17], v[16:17]
	s_waitcnt lgkmcnt(0)
	v_pk_mul_f32 v[6:7], v[12:13], v[12:13]
	v_pk_mul_f32 v[0:1], v[18:19], v[18:19]
	v_pk_mul_f32 v[2:3], v[14:15], v[14:15]
	v_mov_b32_e32 v8, v4
	v_mov_b32_e32 v9, v6
	v_mov_b32_e32 v6, v5
	v_pk_add_f32 v[4:5], v[8:9], v[6:7]
	v_mov_b32_e32 v6, v0
	v_mov_b32_e32 v7, v2
	v_pk_add_f32 v[4:5], v[4:5], v[6:7]
	v_mov_b32_e32 v2, v1
	v_pk_add_f32 v[66:67], v[4:5], v[2:3]
	ds_read_b128 v[4:7], v173 offset:96
	ds_read_b128 v[0:3], v173 offset:112
	s_waitcnt lgkmcnt(1)
	v_pk_mul_f32 v[20:21], v[4:5], v[4:5]
	s_waitcnt lgkmcnt(0)
	v_pk_mul_f32 v[22:23], v[0:1], v[0:1]
	v_pk_mul_f32 v[8:9], v[6:7], v[6:7]
	v_pk_mul_f32 v[10:11], v[2:3], v[2:3]
	v_mov_b32_e32 v24, v20
	v_mov_b32_e32 v25, v22
	v_mov_b32_e32 v22, v21
	v_pk_add_f32 v[20:21], v[24:25], v[22:23]
	v_mov_b32_e32 v22, v8
	v_mov_b32_e32 v23, v10
	v_mov_b32_e32 v10, v9
	v_lshl_add_u64 v[8:9], v[156:157], 0, s[46:47]
	v_lshlrev_b64 v[8:9], 8, v[8:9]
	v_pk_add_f32 v[20:21], v[20:21], v[22:23]
	v_lshl_add_u64 v[28:29], v[150:151], 0, v[8:9]
	v_pk_add_f32 v[68:69], v[20:21], v[10:11]
	global_load_dwordx4 v[8:11], v[28:29], off offset:48
	global_load_dwordx4 v[20:23], v[28:29], off offset:32
	global_load_dwordx4 v[24:27], v[28:29], off offset:16
	global_load_dwordx4 v[70:73], v[28:29], off
	ds_read_b128 v[48:51], v173
	ds_read_b128 v[40:43], v173 offset:16
	ds_read_b128 v[32:35], v173 offset:32
	ds_read_b128 v[28:31], v173 offset:48
	global_load_dwordx4 v[36:39], v[154:155], off offset:16
	global_load_dwordx4 v[44:47], v[154:155], off
	global_load_dwordx4 v[192:195], v[154:155], off offset:48
	global_load_dwordx4 v[196:199], v[154:155], off offset:32
	global_load_dwordx4 v[200:203], v[154:155], off offset:80
	global_load_dwordx4 v[204:207], v[154:155], off offset:64
	global_load_dwordx4 v[208:211], v[154:155], off offset:112
	global_load_dwordx4 v[212:215], v[154:155], off offset:96
	s_waitcnt lgkmcnt(3)
	v_mov_b32_e32 v84, v49
	s_waitcnt lgkmcnt(2)
	v_mov_b32_e32 v85, v41
	v_mov_b32_e32 v78, v48
	v_mov_b32_e32 v79, v40
	v_pk_mul_f32 v[84:85], v[84:85], v[84:85]
	s_waitcnt lgkmcnt(1)
	v_mov_b32_e32 v90, v33
	v_pk_fma_f32 v[78:79], v[78:79], v[78:79], v[84:85]
	s_waitcnt lgkmcnt(0)
	v_mov_b32_e32 v91, v29
	v_mov_b32_e32 v74, v51
	v_mov_b32_e32 v75, v43
	v_mov_b32_e32 v88, v32
	v_mov_b32_e32 v89, v28
	v_pk_mul_f32 v[90:91], v[90:91], v[90:91]
	v_mov_b32_e32 v86, v35
	v_pk_fma_f32 v[88:89], v[88:89], v[88:89], v[90:91]
	v_mov_b32_e32 v87, v31
	v_add_u32_e32 v156, 64, v156
	s_waitcnt vmcnt(8)
	v_lshlrev_b32_e32 v80, 16, v71
	v_and_b32_e32 v81, 0xffff0000, v71
	v_lshlrev_b32_e32 v82, 16, v70
	v_and_b32_e32 v83, 0xffff0000, v70
	v_mov_b32_e32 v70, v50
	v_mov_b32_e32 v71, v42
	v_pk_fma_f32 v[70:71], v[70:71], v[70:71], v[78:79]
	v_lshlrev_b32_e32 v76, 16, v72
	v_and_b32_e32 v77, 0xffff0000, v72
	v_pk_fma_f32 v[84:85], v[74:75], v[74:75], v[70:71]
	v_lshlrev_b32_e32 v78, 16, v73
	v_and_b32_e32 v79, 0xffff0000, v73
	v_lshlrev_b32_e32 v72, 16, v25
	v_and_b32_e32 v73, 0xffff0000, v25
	v_lshlrev_b32_e32 v74, 16, v24
	v_and_b32_e32 v75, 0xffff0000, v24
	v_mov_b32_e32 v24, v34
	v_mov_b32_e32 v25, v30
	v_pk_fma_f32 v[24:25], v[24:25], v[24:25], v[88:89]
	v_lshlrev_b32_e32 v70, 16, v26
	v_and_b32_e32 v71, 0xffff0000, v26
	v_pk_fma_f32 v[24:25], v[86:87], v[86:87], v[24:25]
	v_add_f32_e32 v26, v84, v85
	v_add_f32_e32 v24, v26, v24
	v_add_f32_e32 v24, v24, v25
	v_add_f32_e32 v24, v24, v66
	v_add_f32_e32 v24, v24, v67
	v_add_f32_e32 v24, v24, v68
	v_add_f32_e32 v24, v24, v69
	ds_bpermute_b32 v25, v174, v24
	v_lshlrev_b32_e32 v26, 16, v27
	v_and_b32_e32 v27, 0xffff0000, v27
	s_waitcnt lgkmcnt(0)
	v_add_f32_e32 v24, v24, v25
	ds_bpermute_b32 v25, v175, v24
	s_waitcnt lgkmcnt(0)
	v_add_f32_e32 v24, v24, v25
	v_fmamk_f32 v24, v24, 0x3c000000, v161
	v_cmp_gt_f32_e64 s[36:37], s70, v24
	v_mul_f32_e32 v25, 0x4b800000, v24
	s_nop 0
	v_cndmask_b32_e64 v24, v24, v25, s[36:37]
	v_rsq_f32_e32 v24, v24
	s_nop 0
	v_mul_f32_e32 v25, 0x45800000, v24
	v_cndmask_b32_e64 v24, v24, v25, s[36:37]
	v_pk_mul_f32 v[48:49], v[48:49], v[24:25] op_sel_hi:[1,0]
	v_pk_mul_f32 v[40:41], v[40:41], v[24:25] op_sel_hi:[1,0]
	s_waitcnt vmcnt(6)
	v_pk_mul_f32 v[44:45], v[44:45], v[48:49]
	v_pk_mul_f32 v[48:49], v[50:51], v[24:25] op_sel_hi:[1,0]
	v_pk_mul_f32 v[36:37], v[36:37], v[40:41]
	v_pk_mul_f32 v[46:47], v[46:47], v[48:49]
	v_pk_mul_f32 v[44:45], v[44:45], v[82:83]
	v_pk_mul_f32 v[46:47], v[46:47], v[80:81]
	v_pk_mul_f32 v[36:37], v[36:37], v[76:77]
	v_cvt_pk_bf16_f32 v44, v44, v45
	v_cvt_pk_bf16_f32 v45, v46, v47
	v_cvt_pk_bf16_f32 v46, v36, v37
	v_pk_mul_f32 v[36:37], v[42:43], v[24:25] op_sel_hi:[1,0]
	v_pk_mul_f32 v[32:33], v[32:33], v[24:25] op_sel_hi:[1,0]
	v_pk_mul_f32 v[36:37], v[36:37], v[38:39]
	v_pk_mul_f32 v[34:35], v[34:35], v[24:25] op_sel_hi:[1,0]
	v_pk_mul_f32 v[36:37], v[36:37], v[78:79]
	v_pk_mul_f32 v[28:29], v[28:29], v[24:25] op_sel_hi:[1,0]
	v_cvt_pk_bf16_f32 v47, v36, v37
	global_store_dwordx4 v[64:65], v[44:47], off
	v_pk_mul_f32 v[16:17], v[16:17], v[24:25] op_sel_hi:[1,0]
	v_pk_mul_f32 v[18:19], v[18:19], v[24:25] op_sel_hi:[1,0]
	v_pk_mul_f32 v[12:13], v[12:13], v[24:25] op_sel_hi:[1,0]
	v_pk_mul_f32 v[4:5], v[4:5], v[24:25] op_sel_hi:[1,0]
	v_pk_mul_f32 v[6:7], v[6:7], v[24:25] op_sel_hi:[1,0]
	v_pk_mul_f32 v[0:1], v[0:1], v[24:25] op_sel_hi:[1,0]
	s_waitcnt vmcnt(6)
	v_pk_mul_f32 v[28:29], v[28:29], v[192:193]
	s_waitcnt vmcnt(5)
	v_pk_mul_f32 v[32:33], v[32:33], v[196:197]
	v_pk_mul_f32 v[34:35], v[34:35], v[198:199]
	v_pk_mul_f32 v[32:33], v[32:33], v[74:75]
	v_pk_mul_f32 v[34:35], v[34:35], v[72:73]
	v_pk_mul_f32 v[28:29], v[28:29], v[70:71]
	v_cvt_pk_bf16_f32 v32, v32, v33
	v_cvt_pk_bf16_f32 v33, v34, v35
	v_cvt_pk_bf16_f32 v34, v28, v29
	v_pk_mul_f32 v[28:29], v[30:31], v[24:25] op_sel_hi:[1,0]
	s_nop 0
	v_pk_mul_f32 v[28:29], v[28:29], v[194:195]
	s_nop 0
	v_pk_mul_f32 v[26:27], v[28:29], v[26:27]
	s_nop 0
	v_cvt_pk_bf16_f32 v35, v26, v27
	global_store_dwordx4 v[64:65], v[32:35], off offset:16
	s_nop 0
	s_waitcnt vmcnt(5)
	v_pk_mul_f32 v[12:13], v[12:13], v[200:201]
	s_waitcnt vmcnt(4)
	v_pk_mul_f32 v[16:17], v[16:17], v[204:205]
	v_lshlrev_b32_e32 v30, 16, v20
	v_and_b32_e32 v31, 0xffff0000, v20
	v_pk_mul_f32 v[18:19], v[18:19], v[206:207]
	v_lshlrev_b32_e32 v20, 16, v21
	v_and_b32_e32 v21, 0xffff0000, v21
	v_pk_mul_f32 v[16:17], v[16:17], v[30:31]
	v_pk_mul_f32 v[18:19], v[18:19], v[20:21]
	v_cvt_pk_bf16_f32 v16, v16, v17
	v_cvt_pk_bf16_f32 v17, v18, v19
	v_lshlrev_b32_e32 v18, 16, v22
	v_and_b32_e32 v19, 0xffff0000, v22
	v_pk_mul_f32 v[12:13], v[12:13], v[18:19]
	s_nop 0
	v_cvt_pk_bf16_f32 v18, v12, v13
	v_pk_mul_f32 v[12:13], v[14:15], v[24:25] op_sel_hi:[1,0]
	v_lshlrev_b32_e32 v14, 16, v23
	v_pk_mul_f32 v[12:13], v[12:13], v[202:203]
	v_and_b32_e32 v15, 0xffff0000, v23
	v_pk_mul_f32 v[12:13], v[12:13], v[14:15]
	s_nop 0
	v_cvt_pk_bf16_f32 v19, v12, v13
	global_store_dwordx4 v[64:65], v[16:19], off offset:32
	s_nop 0
	s_waitcnt vmcnt(4)
	v_pk_mul_f32 v[0:1], v[0:1], v[208:209]
	s_waitcnt vmcnt(3)
	v_pk_mul_f32 v[4:5], v[4:5], v[212:213]
	v_lshlrev_b32_e32 v16, 16, v8
	v_and_b32_e32 v17, 0xffff0000, v8
	v_pk_mul_f32 v[6:7], v[6:7], v[214:215]
	v_lshlrev_b32_e32 v8, 16, v9
	v_and_b32_e32 v9, 0xffff0000, v9
	v_pk_mul_f32 v[4:5], v[4:5], v[16:17]
	v_pk_mul_f32 v[6:7], v[6:7], v[8:9]
	v_cvt_pk_bf16_f32 v4, v4, v5
	v_cvt_pk_bf16_f32 v5, v6, v7
	v_lshlrev_b32_e32 v6, 16, v10
	v_and_b32_e32 v7, 0xffff0000, v10
	v_pk_mul_f32 v[0:1], v[0:1], v[6:7]
	s_nop 0
	v_cvt_pk_bf16_f32 v6, v0, v1
	v_pk_mul_f32 v[0:1], v[2:3], v[24:25] op_sel_hi:[1,0]
	v_lshlrev_b32_e32 v2, 16, v11
	v_pk_mul_f32 v[0:1], v[0:1], v[210:211]
	v_and_b32_e32 v3, 0xffff0000, v11
	v_pk_mul_f32 v[0:1], v[0:1], v[2:3]
	s_nop 0
	v_cvt_pk_bf16_f32 v7, v0, v1
	global_store_dwordx4 v[64:65], v[4:7], off offset:48
	s_cbranch_scc1 .LBB0_425

.LBB0_2055:
	s_or_b64 exec, exec, s[0:1]
	v_writelane_b32 v254, s24, 52
	s_and_b32 s0, s24, 0xfffff000
	v_writelane_b32 v254, s0, 53
	s_and_b32 s0, s20, 0xf80
	s_lshl_b32 s46, s16, 3
	s_lshl_b32 s36, s16, 5
	v_writelane_b32 v254, s0, 54
	s_lshl_b32 s0, s16, 10
	v_writelane_b32 v254, s0, 55
	v_and_b32_e32 v101, 31, v25
	s_add_u32 s0, s26, 0x96e0000
	v_ashrrev_i32_e32 v10, 1, v27
	s_addc_u32 s1, s27, 0
	v_and_b32_e32 v11, 0xffffffe0, v10
	v_or_b32_e32 v4, s19, v101
	v_writelane_b32 v254, s0, 56
	v_add_u32_e32 v98, v4, v11
	v_ashrrev_i32_e32 v99, 31, v98
	v_writelane_b32 v254, s1, 57
	s_mul_i32 s0, s18, 0x8100
	s_mov_b32 s1, s37
	v_bfe_u32 v7, v25, 5, 1
	v_lshl_add_u64 v[4:5], v[98:99], 0, s[0:1]
	s_lshl_b32 s0, s18, 3
	v_lshlrev_b32_e32 v100, 2, v7
	s_cmp_eq_u32 s17, 0
	v_sub_u32_e32 v8, 0x80, v11
	v_writelane_b32 v254, s0, 36
	s_cselect_b64 s[0:1], -1, 0
	v_cmp_lt_i32_e32 vcc, v100, v8
	s_and_b64 s[2:3], s[0:1], vcc
	v_or_b32_e32 v9, 1, v100
	v_writelane_b32 v254, s2, 37
	v_cmp_lt_i32_e32 vcc, v9, v8
	v_or_b32_e32 v104, 2, v100
	v_writelane_b32 v254, s3, 38
	s_and_b64 s[2:3], s[0:1], vcc
	v_writelane_b32 v254, s2, 39
	v_cmp_lt_i32_e32 vcc, v104, v8
	v_or_b32_e32 v105, 3, v100
	v_writelane_b32 v254, s3, 40
	s_and_b64 s[2:3], s[0:1], vcc
	v_writelane_b32 v254, s2, 20
	v_cmp_lt_i32_e32 vcc, v105, v8
	v_or_b32_e32 v106, 8, v100
	v_writelane_b32 v254, s3, 21
	s_and_b64 s[2:3], s[0:1], vcc
	v_writelane_b32 v254, s2, 18
	v_cmp_lt_i32_e32 vcc, v106, v8
	v_or_b32_e32 v107, 9, v100
	v_writelane_b32 v254, s3, 19
	s_and_b64 s[2:3], s[0:1], vcc
	v_writelane_b32 v254, s2, 41
	v_cmp_lt_i32_e32 vcc, v107, v8
	v_or_b32_e32 v108, 10, v100
	v_writelane_b32 v254, s3, 42
	s_and_b64 s[2:3], s[0:1], vcc
	v_writelane_b32 v254, s2, 22
	v_cmp_lt_i32_e32 vcc, v108, v8
	v_or_b32_e32 v109, 11, v100
	v_writelane_b32 v254, s3, 23
	s_and_b64 s[2:3], s[0:1], vcc
	v_writelane_b32 v254, s2, 24
	v_cmp_lt_i32_e32 vcc, v109, v8
	v_or_b32_e32 v110, 16, v100
	v_writelane_b32 v254, s3, 25
	s_and_b64 s[2:3], s[0:1], vcc
	v_writelane_b32 v254, s2, 26
	v_cmp_lt_i32_e32 vcc, v110, v8
	v_or_b32_e32 v111, 17, v100
	v_writelane_b32 v254, s3, 27
	s_and_b64 s[2:3], s[0:1], vcc
	v_writelane_b32 v254, s2, 28
	v_cmp_lt_i32_e32 vcc, v111, v8
	v_or_b32_e32 v112, 18, v100
	v_writelane_b32 v254, s3, 29
	s_and_b64 s[2:3], s[0:1], vcc
	v_writelane_b32 v254, s2, 32
	v_cmp_lt_i32_e32 vcc, v112, v8
	v_or_b32_e32 v113, 19, v100
	v_writelane_b32 v254, s3, 33
	s_and_b64 s[2:3], s[0:1], vcc
	v_writelane_b32 v254, s2, 34
	v_cmp_lt_i32_e32 vcc, v113, v8
	v_or_b32_e32 v114, 24, v100
	v_writelane_b32 v254, s3, 35
	s_and_b64 s[2:3], s[0:1], vcc
	v_writelane_b32 v254, s2, 5
	v_cmp_lt_i32_e32 vcc, v114, v8
	v_or_b32_e32 v115, 25, v100
	v_writelane_b32 v254, s3, 6
	s_and_b64 s[2:3], s[0:1], vcc
	v_writelane_b32 v254, s2, 8
	v_cmp_lt_i32_e32 vcc, v115, v8
	v_or_b32_e32 v116, 26, v100
	v_writelane_b32 v254, s3, 9
	s_and_b64 s[2:3], s[0:1], vcc
	v_writelane_b32 v254, s2, 30
	v_cmp_lt_i32_e32 vcc, v116, v8
	v_or_b32_e32 v117, 27, v100
	v_writelane_b32 v254, s3, 31
	s_and_b64 s[2:3], s[0:1], vcc
	v_writelane_b32 v254, s2, 58
	v_cmp_lt_i32_e32 vcc, v117, v8
	v_or_b32_e32 v9, 32, v100
	v_writelane_b32 v254, s3, 59
	s_and_b64 s[2:3], s[0:1], vcc
	v_writelane_b32 v254, s2, 60
	v_cmp_lt_i32_e32 vcc, v9, v8
	v_or_b32_e32 v9, 33, v100
	v_writelane_b32 v254, s3, 61
	s_and_b64 s[2:3], s[0:1], vcc
	v_writelane_b32 v254, s2, 62
	v_or_b32_e32 v118, 0x80, v100
	v_cmp_lt_i32_e32 vcc, v118, v8
	v_writelane_b32 v254, s3, 63
	v_cmp_lt_i32_e64 s[2:3], v9, v8
	s_and_b64 s[2:3], s[0:1], s[2:3]
	v_or_b32_e32 v9, 34, v100
	v_writelane_b32 v255, s2, 0
	v_cmp_lt_i32_e64 s[4:5], v9, v8
	v_or_b32_e32 v9, 35, v100
	v_writelane_b32 v255, s3, 1
	s_and_b64 s[2:3], s[0:1], s[4:5]
	v_writelane_b32 v255, s2, 2
	v_cmp_lt_i32_e64 s[6:7], v9, v8
	v_or_b32_e32 v9, 40, v100
	v_writelane_b32 v255, s3, 3
	s_and_b64 s[2:3], s[0:1], s[6:7]
	v_writelane_b32 v255, s2, 4
	v_cmp_lt_i32_e64 s[8:9], v9, v8
	v_or_b32_e32 v9, 41, v100
	v_writelane_b32 v255, s3, 5
	s_and_b64 s[2:3], s[0:1], s[8:9]
	v_writelane_b32 v255, s2, 6
	v_cmp_lt_i32_e64 s[10:11], v9, v8
	v_or_b32_e32 v9, 42, v100
	v_writelane_b32 v255, s3, 7
	s_and_b64 s[2:3], s[0:1], s[10:11]
	v_writelane_b32 v255, s2, 8
	v_cmp_lt_i32_e64 s[12:13], v9, v8
	v_or_b32_e32 v9, 43, v100
	v_writelane_b32 v255, s3, 9
	s_and_b64 s[2:3], s[0:1], s[12:13]
	v_writelane_b32 v255, s2, 10
	v_cmp_lt_i32_e64 s[14:15], v9, v8
	v_or_b32_e32 v9, 48, v100
	v_writelane_b32 v255, s3, 11
	s_and_b64 s[2:3], s[0:1], s[14:15]
	v_writelane_b32 v255, s2, 12
	v_cmp_lt_i32_e64 s[16:17], v9, v8
	v_or_b32_e32 v9, 49, v100
	v_writelane_b32 v255, s3, 13
	s_and_b64 s[2:3], s[0:1], s[16:17]
	v_writelane_b32 v255, s2, 14
	v_cmp_lt_i32_e64 s[18:19], v9, v8
	v_or_b32_e32 v9, 50, v100
	v_writelane_b32 v255, s3, 15
	s_and_b64 s[2:3], s[0:1], s[18:19]
	v_writelane_b32 v255, s2, 16
	v_cmp_lt_i32_e64 s[20:21], v9, v8
	v_or_b32_e32 v9, 51, v100
	v_writelane_b32 v255, s3, 17
	s_and_b64 s[2:3], s[0:1], s[20:21]
	v_writelane_b32 v255, s2, 18
	v_cmp_lt_i32_e64 s[22:23], v9, v8
	v_or_b32_e32 v9, 56, v100
	v_writelane_b32 v255, s3, 19
	s_and_b64 s[2:3], s[0:1], s[22:23]
	v_writelane_b32 v255, s2, 20
	v_cmp_lt_i32_e64 s[24:25], v9, v8
	v_or_b32_e32 v9, 57, v100
	v_writelane_b32 v255, s3, 21
	s_and_b64 s[2:3], s[0:1], s[24:25]
	v_writelane_b32 v255, s2, 22
	s_mov_b64 s[6:7], s[26:27]
	v_cmp_lt_i32_e64 s[26:27], v9, v8
	v_writelane_b32 v255, s3, 23
	s_and_b64 s[2:3], s[0:1], s[26:27]
	v_or_b32_e32 v9, 58, v100
	v_writelane_b32 v255, s2, 24
	v_cmp_lt_i32_e64 s[28:29], v9, v8
	v_or_b32_e32 v9, 59, v100
	v_writelane_b32 v255, s3, 25
	s_and_b64 s[2:3], s[0:1], s[28:29]
	v_writelane_b32 v255, s2, 26
	v_cmp_lt_i32_e64 s[30:31], v9, v8
	v_or_b32_e32 v9, 64, v100
	v_writelane_b32 v255, s3, 27
	s_and_b64 s[2:3], s[0:1], s[30:31]
	v_writelane_b32 v255, s2, 28
	v_cmp_lt_i32_e64 s[34:35], v9, v8
	v_or_b32_e32 v9, 0x41, v100
	v_writelane_b32 v255, s3, 29
	s_and_b64 s[2:3], s[0:1], s[34:35]
	v_writelane_b32 v255, s2, 30
	v_or_b32_e32 v119, 0x81, v100
	v_or_b32_e32 v120, 0x82, v100
	v_writelane_b32 v255, s3, 31
	s_mov_b64 s[2:3], s[36:37]
	v_cmp_lt_i32_e64 s[36:37], v9, v8
	s_and_b64 s[4:5], s[0:1], s[36:37]
	v_or_b32_e32 v9, 0x42, v100
	v_writelane_b32 v255, s4, 32
	v_cmp_lt_i32_e64 s[38:39], v9, v8
	v_or_b32_e32 v9, 0x43, v100
	v_writelane_b32 v255, s5, 33
	s_and_b64 s[4:5], s[0:1], s[38:39]
	v_writelane_b32 v255, s4, 34
	v_cmp_lt_i32_e64 s[40:41], v9, v8
	v_or_b32_e32 v9, 0x48, v100
	v_writelane_b32 v255, s5, 35
	s_and_b64 s[4:5], s[0:1], s[40:41]
	v_writelane_b32 v255, s4, 36
	v_cmp_lt_i32_e64 s[42:43], v9, v8
	v_or_b32_e32 v9, 0x49, v100
	v_writelane_b32 v255, s5, 37
	s_and_b64 s[4:5], s[0:1], s[42:43]
	v_writelane_b32 v255, s4, 38
	v_cmp_lt_i32_e64 s[44:45], v9, v8
	v_or_b32_e32 v9, 0x4a, v100
	v_writelane_b32 v255, s5, 39
	s_and_b64 s[4:5], s[0:1], s[44:45]
	s_mov_b32 s45, s46
	v_cmp_lt_i32_e64 s[46:47], v9, v8
	v_or_b32_e32 v9, 0x4b, v100
	v_cmp_lt_i32_e64 s[48:49], v9, v8
	v_or_b32_e32 v9, 0x50, v100
	v_cmp_lt_i32_e64 s[50:51], v9, v8
	v_or_b32_e32 v9, 0x51, v100
	v_cmp_lt_i32_e64 s[52:53], v9, v8
	v_or_b32_e32 v9, 0x52, v100
	v_cmp_lt_i32_e64 s[54:55], v9, v8
	v_or_b32_e32 v9, 0x53, v100
	v_cmp_lt_i32_e64 s[56:57], v9, v8
	v_or_b32_e32 v9, 0x58, v100
	v_cmp_lt_i32_e64 s[58:59], v9, v8
	v_or_b32_e32 v9, 0x59, v100
	v_cmp_lt_i32_e64 s[60:61], v9, v8
	v_or_b32_e32 v9, 0x5a, v100
	v_cmp_lt_i32_e64 s[62:63], v9, v8
	v_or_b32_e32 v9, 0x5b, v100
	v_writelane_b32 v255, s4, 40
	v_cmp_lt_i32_e64 s[64:65], v9, v8
	v_or_b32_e32 v9, 0x60, v100
	v_writelane_b32 v255, s5, 41
	s_and_b64 s[4:5], s[0:1], s[46:47]
	v_cmp_lt_i32_e64 s[66:67], v9, v8
	v_or_b32_e32 v9, 0x61, v100
	v_writelane_b32 v255, s4, 42
	v_cmp_lt_i32_e64 s[68:69], v9, v8
	v_or_b32_e32 v9, 0x62, v100
	s_and_b64 s[42:43], s[0:1], vcc
	v_cmp_lt_i32_e32 vcc, v119, v8
	v_writelane_b32 v255, s5, 43
	v_cmp_lt_i32_e64 s[70:71], v9, v8
	v_or_b32_e32 v9, 0x63, v100
	s_and_b64 s[4:5], s[0:1], vcc
	v_cmp_lt_i32_e32 vcc, v120, v8
	v_or_b32_e32 v121, 0x83, v100
	s_and_b64 s[36:37], s[0:1], s[48:49]
	v_cmp_lt_i32_e64 s[72:73], v9, v8
	v_or_b32_e32 v9, 0x68, v100
	s_and_b64 s[48:49], s[0:1], vcc
	v_cmp_lt_i32_e32 vcc, v121, v8
	v_or_b32_e32 v122, 0x88, v100
	v_cmp_lt_i32_e64 s[74:75], v9, v8
	v_or_b32_e32 v9, 0x69, v100
	s_and_b64 s[8:9], s[0:1], vcc
	v_cmp_lt_i32_e32 vcc, v122, v8
	v_or_b32_e32 v123, 0x89, v100
	v_cmp_lt_i32_e64 s[76:77], v9, v8
	v_or_b32_e32 v9, 0x6a, v100
	s_and_b64 s[10:11], s[0:1], vcc
	v_cmp_lt_i32_e32 vcc, v123, v8
	v_or_b32_e32 v124, 0x8a, v100
	v_cmp_lt_i32_e64 s[78:79], v9, v8
	v_or_b32_e32 v9, 0x6b, v100
	s_and_b64 s[12:13], s[0:1], vcc
	v_cmp_lt_i32_e32 vcc, v124, v8
	v_or_b32_e32 v125, 0x8b, v100
	v_cmp_lt_i32_e64 s[80:81], v9, v8
	v_or_b32_e32 v9, 0x70, v100
	s_and_b64 s[14:15], s[0:1], vcc
	v_cmp_lt_i32_e32 vcc, v125, v8
	v_or_b32_e32 v126, 0x90, v100
	v_cmp_lt_i32_e64 s[82:83], v9, v8
	v_or_b32_e32 v9, 0x71, v100
	s_and_b64 s[16:17], s[0:1], vcc
	v_cmp_lt_i32_e32 vcc, v126, v8
	v_or_b32_e32 v127, 0x91, v100
	v_cmp_lt_i32_e64 s[84:85], v9, v8
	v_or_b32_e32 v9, 0x72, v100
	s_and_b64 s[18:19], s[0:1], vcc
	v_cmp_lt_i32_e32 vcc, v127, v8
	v_or_b32_e32 v128, 0x92, v100
	v_cmp_lt_i32_e64 s[86:87], v9, v8
	v_or_b32_e32 v9, 0x73, v100
	s_and_b64 s[20:21], s[0:1], vcc
	v_cmp_lt_i32_e32 vcc, v128, v8
	v_or_b32_e32 v129, 0x93, v100
	v_cmp_lt_i32_e64 s[88:89], v9, v8
	v_or_b32_e32 v9, 0x78, v100
	s_and_b64 s[22:23], s[0:1], vcc
	v_cmp_lt_i32_e32 vcc, v129, v8
	v_or_b32_e32 v130, 0x98, v100
	v_cmp_lt_i32_e64 s[90:91], v9, v8
	v_or_b32_e32 v9, 0x79, v100
	s_and_b64 s[24:25], s[0:1], vcc
	v_cmp_lt_i32_e32 vcc, v130, v8
	v_or_b32_e32 v131, 0x99, v100
	v_cmp_lt_i32_e64 s[92:93], v9, v8
	v_or_b32_e32 v9, 0x7a, v100
	s_and_b64 s[26:27], s[0:1], vcc
	v_cmp_lt_i32_e32 vcc, v131, v8
	v_or_b32_e32 v132, 0x9a, v100
	v_cmp_lt_i32_e64 s[94:95], v9, v8
	v_or_b32_e32 v9, 0x7b, v100
	s_and_b64 s[28:29], s[0:1], vcc
	v_cmp_lt_i32_e32 vcc, v132, v8
	v_or_b32_e32 v133, 0x9b, v100
	v_cmp_lt_i32_e64 s[96:97], v9, v8
	s_and_b64 s[30:31], s[0:1], vcc
	v_cmp_lt_i32_e32 vcc, v133, v8
	s_and_b64 s[50:51], s[0:1], s[50:51]
	s_and_b64 s[52:53], s[0:1], s[52:53]
	s_and_b64 s[54:55], s[0:1], s[54:55]
	s_and_b64 s[56:57], s[0:1], s[56:57]
	s_and_b64 s[58:59], s[0:1], s[58:59]
	s_and_b64 s[60:61], s[0:1], s[60:61]
	s_and_b64 s[62:63], s[0:1], s[62:63]
	s_and_b64 s[64:65], s[0:1], s[64:65]
	s_and_b64 s[66:67], s[0:1], s[66:67]
	s_and_b64 s[68:69], s[0:1], s[68:69]
	s_and_b64 s[70:71], s[0:1], s[70:71]
	s_and_b64 s[72:73], s[0:1], s[72:73]
	s_and_b64 s[74:75], s[0:1], s[74:75]
	s_and_b64 s[76:77], s[0:1], s[76:77]
	s_and_b64 s[78:79], s[0:1], s[78:79]
	s_and_b64 s[80:81], s[0:1], s[80:81]
	s_and_b64 s[82:83], s[0:1], s[82:83]
	s_and_b64 s[84:85], s[0:1], s[84:85]
	s_and_b64 s[86:87], s[0:1], s[86:87]
	s_and_b64 s[88:89], s[0:1], s[88:89]
	s_and_b64 s[90:91], s[0:1], s[90:91]
	s_and_b64 s[92:93], s[0:1], s[92:93]
	s_and_b64 s[94:95], s[0:1], s[94:95]
	s_and_b64 s[96:97], s[0:1], s[96:97]
	s_and_b64 s[34:35], s[0:1], vcc
	v_readlane_b32 s0, v254, 53
	v_readlane_b32 s1, v254, 54
	s_or_b32 s0, s0, s1
	v_add_u32_e32 v8, s0, v11
	v_or_b32_e32 v8, v8, v101
	v_ashrrev_i32_e32 v9, 31, v8
	v_lshlrev_b32_e32 v134, 3, v7
	v_lshlrev_b64 v[8:9], 12, v[8:9]
	v_readlane_b32 s0, v254, 55
	v_lshl_add_u32 v6, v26, 1, v6
	s_waitcnt vmcnt(0)
	ds_write_b16 v6, v0 offset:36864
	ds_write_b16_d16_hi v6, v0 offset:37400
	ds_write_b16 v6, v1 offset:37936
	ds_write_b16_d16_hi v6, v1 offset:38472
	ds_write_b16 v6, v2 offset:39008
	ds_write_b16_d16_hi v6, v2 offset:39544
	ds_write_b16 v6, v3 offset:40080
	ds_write_b16_d16_hi v6, v3 offset:40616
	v_or3_b32 v8, v8, s0, v134
	v_readlane_b32 s0, v254, 56
	v_lshlrev_b64 v[0:1], 9, v[4:5]
	v_readlane_b32 s1, v254, 57
	v_lshlrev_b32_e32 v96, 4, v7
	s_waitcnt lgkmcnt(0)
	v_lshl_add_u64 v[0:1], s[0:1], 0, v[0:1]
	v_lshl_add_u64 v[0:1], v[0:1], 0, v[96:97]
	s_barrier
	global_load_dwordx4 v[80:83], v[0:1], off
	global_load_dwordx4 v[84:87], v[0:1], off offset:32
	global_load_dwordx4 v[88:91], v[0:1], off offset:64
	global_load_dwordx4 v[92:95], v[0:1], off offset:96
	s_mov_b64 s[46:47], s[0:1]
	s_movk_i32 s0, 0xffe0
	v_bfi_b32 v0, s0, v10, v25
	v_readlane_b32 s0, v254, 17
	v_lshlrev_b32_e32 v2, 1, v11
	s_movk_i32 s1, 0x90
	v_lshl_add_u64 v[8:9], s[6:7], 0, v[8:9]
	v_add_u32_e32 v1, s0, v96
	v_mul_lo_u32 v0, v0, s1
	v_mul_u32_u24_e32 v3, 0x218, v101
	v_add3_u32 v2, s0, v2, v134
	s_mov_b64 s[0:1], 0x15860040
	v_readlane_b32 s40, v254, 15
	s_mov_b64 s[6:7], s[36:37]
	v_lshl_add_u64 v[102:103], v[8:9], 0, s[0:1]
	v_add_u32_e32 v135, v1, v0
	v_add_u32_e32 v136, v2, v3
	s_mov_b32 s38, 0
	s_mov_b64 s[36:37], s[2:3]
	v_readlane_b32 s41, v254, 16
	v_readlane_b32 s44, v254, 50
	s_waitcnt vmcnt(0)
.LBB0_2056:
	v_mov_b32_e32 v96, v101
	ds_read_b128 v[0:3], v135
	ds_read_b128 v[4:7], v135 offset:32
	s_load_dwordx2 s[0:1], s[40:41], 0x80
	s_add_i32 s39, s45, s38
	s_waitcnt vmcnt(11) lgkmcnt(0)
	v_mfma_f32_32x32x16_bf16 v[64:79], v[0:3], v[80:83], 0
	ds_read_b128 v[0:3], v135 offset:64
	s_add_u32 s0, s0, s36
	s_addc_u32 s1, s1, s37
	s_add_i32 s38, s38, 1
	s_waitcnt vmcnt(10)
	v_mfma_f32_32x32x16_bf16 v[64:79], v[4:7], v[84:87], v[64:79]
	s_waitcnt vmcnt(9) lgkmcnt(0)
	v_mfma_f32_32x32x16_bf16 v[64:79], v[0:3], v[88:91], v[64:79]
	ds_read_b128 v[0:3], v135 offset:96
	s_waitcnt vmcnt(8) lgkmcnt(0)
	v_mfma_f32_32x32x16_bf16 v[64:79], v[0:3], v[92:95], v[64:79]
	ds_read_b128 v[0:3], v135 offset:4608
	s_waitcnt lgkmcnt(0)
	v_mfma_f32_32x32x16_bf16 v[48:63], v[0:3], v[80:83], 0
	ds_read_b128 v[0:3], v135 offset:4640
	s_waitcnt lgkmcnt(0)
	v_mfma_f32_32x32x16_bf16 v[48:63], v[0:3], v[84:87], v[48:63]
	ds_read_b128 v[0:3], v135 offset:4672
	s_waitcnt lgkmcnt(0)
	v_mfma_f32_32x32x16_bf16 v[48:63], v[0:3], v[88:91], v[48:63]
	ds_read_b128 v[0:3], v135 offset:4704
	s_waitcnt lgkmcnt(0)
	v_mfma_f32_32x32x16_bf16 v[48:63], v[0:3], v[92:95], v[48:63]
	ds_read_b128 v[0:3], v135 offset:9216
	s_waitcnt lgkmcnt(0)
	v_mfma_f32_32x32x16_bf16 v[32:47], v[0:3], v[80:83], 0
	ds_read_b128 v[0:3], v135 offset:9248
	s_waitcnt lgkmcnt(0)
	v_mfma_f32_32x32x16_bf16 v[32:47], v[0:3], v[84:87], v[32:47]
	ds_read_b128 v[0:3], v135 offset:9280
	s_waitcnt lgkmcnt(0)
	v_mfma_f32_32x32x16_bf16 v[32:47], v[0:3], v[88:91], v[32:47]
	ds_read_b128 v[0:3], v135 offset:9312
	s_waitcnt lgkmcnt(0)
	v_mfma_f32_32x32x16_bf16 v[32:47], v[0:3], v[92:95], v[32:47]
	ds_read_b128 v[0:3], v135 offset:13824
	s_waitcnt lgkmcnt(0)
	v_mfma_f32_32x32x16_bf16 v[16:31], v[0:3], v[80:83], 0
	ds_read_b128 v[0:3], v135 offset:13856
	s_waitcnt lgkmcnt(0)
	v_mfma_f32_32x32x16_bf16 v[16:31], v[0:3], v[84:87], v[16:31]
	ds_read_b128 v[0:3], v135 offset:13888
	s_waitcnt lgkmcnt(0)
	v_mfma_f32_32x32x16_bf16 v[16:31], v[0:3], v[88:91], v[16:31]
	ds_read_b128 v[0:3], v135 offset:13920
	s_waitcnt lgkmcnt(0)
	v_mfma_f32_32x32x16_bf16 v[16:31], v[0:3], v[92:95], v[16:31]
	ds_read_b128 v[0:3], v135 offset:18432
	s_waitcnt lgkmcnt(0)
	v_mfma_f32_32x32x16_bf16 v[0:15], v[0:3], v[80:83], 0
	ds_read_b128 v[80:83], v135 offset:18464
	s_waitcnt lgkmcnt(0)
	v_mfma_f32_32x32x16_bf16 v[0:15], v[80:83], v[84:87], v[0:15]
	ds_read_b128 v[80:83], v135 offset:18496
	s_waitcnt lgkmcnt(0)
	v_mfma_f32_32x32x16_bf16 v[0:15], v[80:83], v[88:91], v[0:15]
	ds_read_b128 v[80:83], v135 offset:18528
	s_waitcnt lgkmcnt(0)
	v_mfma_f32_32x32x16_bf16 v[0:15], v[80:83], v[92:95], v[0:15]
	global_load_dword v80, v97, s[0:1]
	v_add_u32_e32 v94, 0x80, v96
	v_cmp_le_i32_e64 s[0:1], v100, v96
	v_cmp_gt_i32_e32 vcc, v100, v94
	s_or_b64 s[0:1], s[0:1], vcc
	v_readlane_b32 vcc_lo, v254, 37
	v_readlane_b32 vcc_hi, v254, 38
	s_or_b64 vcc, s[0:1], vcc
	v_cmp_ge_i32_e64 s[0:1], v100, v94
	v_cndmask_b32_e32 v64, v64, v200, vcc
	v_cmp_lt_i32_e32 vcc, v100, v96
	s_or_b64 s[0:1], vcc, s[0:1]
	v_readlane_b32 vcc_lo, v254, 39
	v_readlane_b32 vcc_hi, v254, 40
	s_or_b64 vcc, s[0:1], vcc
	v_cmp_gt_i32_e64 s[0:1], v104, v94
	v_cndmask_b32_e32 v65, v65, v200, vcc
	v_cmp_le_i32_e32 vcc, v104, v96
	s_or_b64 s[0:1], vcc, s[0:1]
	v_readlane_b32 vcc_lo, v254, 20
	v_readlane_b32 vcc_hi, v254, 21
	s_or_b64 vcc, s[0:1], vcc
	v_cmp_gt_i32_e64 s[0:1], v105, v94
	v_cndmask_b32_e32 v66, v66, v200, vcc
	v_cmp_le_i32_e32 vcc, v105, v96
	s_or_b64 s[0:1], vcc, s[0:1]
	v_readlane_b32 vcc_lo, v254, 18
	v_readlane_b32 vcc_hi, v254, 19
	s_or_b64 vcc, s[0:1], vcc
	v_cmp_gt_i32_e64 s[0:1], v106, v94
	v_cndmask_b32_e32 v67, v67, v200, vcc
	v_cmp_le_i32_e32 vcc, v106, v96
	s_or_b64 s[0:1], vcc, s[0:1]
	v_readlane_b32 vcc_lo, v254, 41
	v_readlane_b32 vcc_hi, v254, 42
	s_or_b64 vcc, s[0:1], vcc
	v_cmp_gt_i32_e64 s[0:1], v107, v94
	v_cndmask_b32_e32 v68, v68, v200, vcc
	v_cmp_le_i32_e32 vcc, v107, v96
	s_or_b64 s[0:1], vcc, s[0:1]
	v_readlane_b32 vcc_lo, v254, 22
	v_readlane_b32 vcc_hi, v254, 23
	s_or_b64 vcc, s[0:1], vcc
	v_cmp_gt_i32_e64 s[0:1], v108, v94
	v_cndmask_b32_e32 v69, v69, v200, vcc
	v_cmp_le_i32_e32 vcc, v108, v96
	s_or_b64 s[0:1], vcc, s[0:1]
	v_readlane_b32 vcc_lo, v254, 24
	v_readlane_b32 vcc_hi, v254, 25
	s_or_b64 vcc, s[0:1], vcc
	v_cmp_gt_i32_e64 s[0:1], v109, v94
	v_cndmask_b32_e32 v70, v70, v200, vcc
	v_cmp_le_i32_e32 vcc, v109, v96
	s_or_b64 s[0:1], vcc, s[0:1]
	v_readlane_b32 vcc_lo, v254, 26
	v_readlane_b32 vcc_hi, v254, 27
	s_or_b64 vcc, s[0:1], vcc
	v_cmp_gt_i32_e64 s[0:1], v110, v94
	v_cndmask_b32_e32 v71, v71, v200, vcc
	v_cmp_le_i32_e32 vcc, v110, v96
	s_or_b64 s[0:1], vcc, s[0:1]
	v_readlane_b32 vcc_lo, v254, 28
	v_readlane_b32 vcc_hi, v254, 29
	s_or_b64 vcc, s[0:1], vcc
	v_cmp_gt_i32_e64 s[0:1], v111, v94
	v_cndmask_b32_e32 v72, v72, v200, vcc
	v_cmp_le_i32_e32 vcc, v111, v96
	s_or_b64 s[0:1], vcc, s[0:1]
	v_readlane_b32 vcc_lo, v254, 32
	v_readlane_b32 vcc_hi, v254, 33
	s_or_b64 vcc, s[0:1], vcc
	v_cmp_gt_i32_e64 s[0:1], v112, v94
	v_cndmask_b32_e32 v73, v73, v200, vcc
	v_cmp_le_i32_e32 vcc, v112, v96
	s_or_b64 s[0:1], vcc, s[0:1]
	v_readlane_b32 vcc_lo, v254, 34
	v_readlane_b32 vcc_hi, v254, 35
	s_or_b64 vcc, s[0:1], vcc
	v_cmp_gt_i32_e64 s[0:1], v113, v94
	v_cndmask_b32_e32 v74, v74, v200, vcc
	v_cmp_le_i32_e32 vcc, v113, v96
	s_or_b64 s[0:1], vcc, s[0:1]
	v_readlane_b32 vcc_lo, v254, 5
	v_readlane_b32 vcc_hi, v254, 6
	s_or_b64 vcc, s[0:1], vcc
	v_cmp_gt_i32_e64 s[0:1], v114, v94
	v_cndmask_b32_e32 v75, v75, v200, vcc
	v_cmp_le_i32_e32 vcc, v114, v96
	s_or_b64 s[0:1], vcc, s[0:1]
	v_readlane_b32 vcc_lo, v254, 8
	v_readlane_b32 vcc_hi, v254, 9
	s_or_b64 vcc, s[0:1], vcc
	v_cmp_gt_i32_e64 s[0:1], v115, v94
	v_cndmask_b32_e32 v76, v76, v200, vcc
	v_cmp_le_i32_e32 vcc, v115, v96
	s_or_b64 s[0:1], vcc, s[0:1]
	v_readlane_b32 vcc_lo, v254, 30
	v_readlane_b32 vcc_hi, v254, 31
	s_or_b64 vcc, s[0:1], vcc
	v_cmp_gt_i32_e64 s[0:1], v116, v94
	v_cndmask_b32_e32 v77, v77, v200, vcc
	v_cmp_le_i32_e32 vcc, v116, v96
	s_or_b64 s[0:1], vcc, s[0:1]
	v_readlane_b32 vcc_lo, v254, 58
	v_readlane_b32 vcc_hi, v254, 59
	s_or_b64 vcc, s[0:1], vcc
	v_cmp_gt_i32_e64 s[0:1], v117, v94
	v_cndmask_b32_e32 v85, v78, v200, vcc
	v_cmp_le_i32_e32 vcc, v117, v96
	s_or_b64 s[0:1], vcc, s[0:1]
	v_readlane_b32 vcc_lo, v254, 60
	v_readlane_b32 vcc_hi, v254, 61
	s_or_b64 vcc, s[0:1], vcc
	v_readlane_b32 s0, v254, 62
	v_readlane_b32 s1, v254, 63
	s_waitcnt vmcnt(0)
	v_max3_f32 v81, v80, v64, v65
	v_max3_f32 v81, v81, v66, v67
	v_cndmask_b32_e64 v93, v48, v200, s[0:1]
	v_readlane_b32 s0, v255, 0
	v_readlane_b32 s1, v255, 1
	v_max3_f32 v81, v81, v68, v69
	v_max3_f32 v81, v81, v70, v71
	v_cndmask_b32_e64 v90, v49, v200, s[0:1]
	v_readlane_b32 s0, v255, 2
	v_readlane_b32 s1, v255, 3
	v_max3_f32 v81, v81, v72, v73
	v_max3_f32 v81, v81, v74, v75
	v_cndmask_b32_e64 v91, v50, v200, s[0:1]
	v_readlane_b32 s0, v255, 4
	v_readlane_b32 s1, v255, 5
	v_max3_f32 v81, v81, v76, v77
	v_cndmask_b32_e32 v92, v79, v200, vcc
	v_cndmask_b32_e64 v88, v51, v200, s[0:1]
	v_readlane_b32 s0, v255, 6
	v_readlane_b32 s1, v255, 7
	v_max3_f32 v78, v81, v85, v92
	v_max3_f32 v48, v78, v93, v90
	v_cndmask_b32_e64 v89, v52, v200, s[0:1]
	v_readlane_b32 s0, v255, 8
	v_readlane_b32 s1, v255, 9
	v_cmp_le_i32_e32 vcc, v118, v96
	v_max3_f32 v48, v48, v91, v88
	v_cndmask_b32_e64 v86, v53, v200, s[0:1]
	v_readlane_b32 s0, v255, 10
	v_readlane_b32 s1, v255, 11
	v_max3_f32 v48, v48, v89, v86
	v_cndmask_b32_e64 v52, v39, v200, s[6:7]
	v_cndmask_b32_e64 v87, v54, v200, s[0:1]
	v_readlane_b32 s0, v255, 12
	v_readlane_b32 s1, v255, 13
	v_cndmask_b32_e64 v51, v40, v200, s[50:51]
	v_cndmask_b32_e64 v50, v41, v200, s[52:53]
	v_cndmask_b32_e64 v83, v55, v200, s[0:1]
	v_readlane_b32 s0, v255, 14
	v_readlane_b32 s1, v255, 15
	v_max3_f32 v48, v48, v87, v83
	v_cndmask_b32_e64 v49, v42, v200, s[54:55]
	v_cndmask_b32_e64 v84, v56, v200, s[0:1]
	v_readlane_b32 s0, v255, 16
	v_readlane_b32 s1, v255, 17
	v_cndmask_b32_e64 v42, v45, v200, s[60:61]
	v_cndmask_b32_e64 v41, v46, v200, s[62:63]
	v_cndmask_b32_e64 v81, v57, v200, s[0:1]
	v_readlane_b32 s0, v255, 18
	v_readlane_b32 s1, v255, 19
	v_max3_f32 v48, v48, v84, v81
	v_cndmask_b32_e64 v40, v47, v200, s[64:65]
	v_cndmask_b32_e64 v82, v58, v200, s[0:1]
	v_readlane_b32 s0, v255, 20
	v_readlane_b32 s1, v255, 21
	v_cndmask_b32_e64 v39, v16, v200, s[66:67]
	s_nop 0
	v_cndmask_b32_e64 v78, v59, v200, s[0:1]
	v_readlane_b32 s0, v255, 22
	v_readlane_b32 s1, v255, 23
	v_max3_f32 v48, v48, v82, v78
	s_nop 0
	v_cndmask_b32_e64 v79, v60, v200, s[0:1]
	v_readlane_b32 s0, v255, 24
	v_readlane_b32 s1, v255, 25
	s_nop 1
	v_cndmask_b32_e64 v61, v61, v200, s[0:1]
	v_readlane_b32 s0, v255, 26
	v_readlane_b32 s1, v255, 27
	v_max3_f32 v48, v48, v79, v61
	s_nop 0
	v_cndmask_b32_e64 v62, v62, v200, s[0:1]
	v_readlane_b32 s0, v255, 28
	v_readlane_b32 s1, v255, 29
	s_nop 1
	v_cndmask_b32_e64 v59, v63, v200, s[0:1]
	v_readlane_b32 s0, v255, 30
	v_readlane_b32 s1, v255, 31
	v_max3_f32 v48, v48, v62, v59
	s_nop 0
	v_cndmask_b32_e64 v60, v32, v200, s[0:1]
	v_readlane_b32 s0, v255, 32
	v_readlane_b32 s1, v255, 33
	s_nop 1
	v_cndmask_b32_e64 v57, v33, v200, s[0:1]
	v_readlane_b32 s0, v255, 34
	v_readlane_b32 s1, v255, 35
	v_max3_f32 v32, v48, v60, v57
	v_cndmask_b32_e64 v48, v43, v200, s[56:57]
	v_cndmask_b32_e64 v58, v34, v200, s[0:1]
	v_readlane_b32 s0, v255, 36
	v_readlane_b32 s1, v255, 37
	v_cndmask_b32_e64 v43, v44, v200, s[58:59]
	v_cndmask_b32_e64 v34, v21, v200, s[76:77]
	v_cndmask_b32_e64 v55, v35, v200, s[0:1]
	v_readlane_b32 s0, v255, 38
	v_readlane_b32 s1, v255, 39
	v_max3_f32 v32, v32, v58, v55
	v_cndmask_b32_e64 v35, v20, v200, s[74:75]
	v_cndmask_b32_e64 v56, v36, v200, s[0:1]
	v_readlane_b32 s0, v255, 40
	v_readlane_b32 s1, v255, 41
	v_cndmask_b32_e64 v36, v19, v200, s[72:73]
	v_cndmask_b32_e64 v33, v22, v200, s[78:79]
	v_cndmask_b32_e64 v53, v37, v200, s[0:1]
	v_readlane_b32 s0, v255, 42
	v_readlane_b32 s1, v255, 43
	v_max3_f32 v32, v32, v56, v53
	v_cndmask_b32_e64 v37, v18, v200, s[70:71]
	v_cndmask_b32_e64 v54, v38, v200, s[0:1]
	v_cmp_gt_i32_e64 s[0:1], v100, v96
	s_or_b64 s[0:1], vcc, s[0:1]
	s_or_b64 vcc, s[0:1], s[42:43]
	v_cndmask_b32_e32 v0, v0, v200, vcc
	v_cmp_le_i32_e32 vcc, v119, v96
	v_cmp_gt_i32_e64 s[0:1], v119, v94
	s_or_b64 s[0:1], vcc, s[0:1]
	s_or_b64 vcc, s[0:1], s[4:5]
	v_cndmask_b32_e32 v1, v1, v200, vcc
	v_cmp_le_i32_e32 vcc, v120, v96
	v_cmp_gt_i32_e64 s[0:1], v120, v94
	s_or_b64 s[0:1], vcc, s[0:1]
	s_or_b64 vcc, s[0:1], s[48:49]
	v_cndmask_b32_e32 v2, v2, v200, vcc
	v_cmp_le_i32_e32 vcc, v121, v96
	v_cmp_gt_i32_e64 s[0:1], v121, v94
	s_or_b64 s[0:1], vcc, s[0:1]
	s_or_b64 vcc, s[0:1], s[8:9]
	v_cndmask_b32_e32 v3, v3, v200, vcc
	v_cmp_le_i32_e32 vcc, v122, v96
	v_cmp_gt_i32_e64 s[0:1], v122, v94
	s_or_b64 s[0:1], vcc, s[0:1]
	s_or_b64 vcc, s[0:1], s[10:11]
	v_cndmask_b32_e32 v4, v4, v200, vcc
	v_cmp_le_i32_e32 vcc, v123, v96
	v_cmp_gt_i32_e64 s[0:1], v123, v94
	s_or_b64 s[0:1], vcc, s[0:1]
	s_or_b64 vcc, s[0:1], s[12:13]
	v_cndmask_b32_e32 v5, v5, v200, vcc
	v_cmp_le_i32_e32 vcc, v124, v96
	v_cmp_gt_i32_e64 s[0:1], v124, v94
	s_or_b64 s[0:1], vcc, s[0:1]
	s_or_b64 vcc, s[0:1], s[14:15]
	v_cndmask_b32_e32 v6, v6, v200, vcc
	v_cmp_le_i32_e32 vcc, v125, v96
	v_cmp_gt_i32_e64 s[0:1], v125, v94
	s_or_b64 s[0:1], vcc, s[0:1]
	s_or_b64 vcc, s[0:1], s[16:17]
	v_cndmask_b32_e32 v7, v7, v200, vcc
	v_cmp_le_i32_e32 vcc, v126, v96
	v_cmp_gt_i32_e64 s[0:1], v126, v94
	s_or_b64 s[0:1], vcc, s[0:1]
	s_or_b64 vcc, s[0:1], s[18:19]
	v_cndmask_b32_e32 v8, v8, v200, vcc
	v_cmp_le_i32_e32 vcc, v127, v96
	v_cmp_gt_i32_e64 s[0:1], v127, v94
	s_or_b64 s[0:1], vcc, s[0:1]
	s_or_b64 vcc, s[0:1], s[20:21]
	v_max3_f32 v32, v32, v54, v52
	v_cndmask_b32_e32 v9, v9, v200, vcc
	v_cmp_le_i32_e32 vcc, v128, v96
	v_cmp_gt_i32_e64 s[0:1], v128, v94
	v_max3_f32 v32, v32, v51, v50
	s_or_b64 s[0:1], vcc, s[0:1]
	v_max3_f32 v32, v32, v49, v48
	s_or_b64 vcc, s[0:1], s[22:23]
	v_max3_f32 v32, v32, v43, v42
	v_cndmask_b32_e32 v10, v10, v200, vcc
	v_cmp_le_i32_e32 vcc, v129, v96
	v_cmp_gt_i32_e64 s[0:1], v129, v94
	v_max3_f32 v32, v32, v41, v40
	v_cndmask_b32_e64 v38, v17, v200, s[68:69]
	s_or_b64 s[0:1], vcc, s[0:1]
	v_max3_f32 v16, v32, v39, v38
	s_or_b64 vcc, s[0:1], s[24:25]
	v_max3_f32 v16, v16, v37, v36
	v_cndmask_b32_e32 v11, v11, v200, vcc
	v_cmp_le_i32_e32 vcc, v130, v96
	v_cmp_gt_i32_e64 s[0:1], v130, v94
	v_max3_f32 v16, v16, v35, v34
	v_cndmask_b32_e64 v32, v23, v200, s[80:81]
	s_or_b64 s[0:1], vcc, s[0:1]
	v_max3_f32 v16, v16, v33, v32
	v_cndmask_b32_e64 v23, v24, v200, s[82:83]
	v_cndmask_b32_e64 v22, v25, v200, s[84:85]
	s_or_b64 vcc, s[0:1], s[26:27]
	v_max3_f32 v16, v16, v23, v22
	v_cndmask_b32_e64 v21, v26, v200, s[86:87]
	v_cndmask_b32_e64 v20, v27, v200, s[88:89]
	v_cndmask_b32_e32 v12, v12, v200, vcc
	v_cmp_le_i32_e32 vcc, v131, v96
	v_cmp_gt_i32_e64 s[0:1], v131, v94
	v_max3_f32 v16, v16, v21, v20
	v_cndmask_b32_e64 v19, v28, v200, s[90:91]
	v_cndmask_b32_e64 v18, v29, v200, s[92:93]
	s_or_b64 s[0:1], vcc, s[0:1]
	v_max3_f32 v24, v16, v19, v18
	v_cndmask_b32_e64 v17, v30, v200, s[94:95]
	v_cndmask_b32_e64 v16, v31, v200, s[96:97]
	s_or_b64 vcc, s[0:1], s[28:29]
	v_max3_f32 v24, v24, v17, v16
	v_cndmask_b32_e32 v13, v13, v200, vcc
	v_cmp_le_i32_e32 vcc, v132, v96
	v_cmp_gt_i32_e64 s[0:1], v132, v94
	v_max3_f32 v24, v24, v0, v1
	s_or_b64 s[0:1], vcc, s[0:1]
	v_max3_f32 v24, v24, v2, v3
	s_or_b64 vcc, s[0:1], s[30:31]
	v_max3_f32 v24, v24, v4, v5
	v_cndmask_b32_e32 v14, v14, v200, vcc
	v_cmp_le_i32_e32 vcc, v133, v96
	v_cmp_gt_i32_e64 s[0:1], v133, v94
	v_max3_f32 v24, v24, v6, v7
	s_or_b64 s[0:1], vcc, s[0:1]
	v_and_b32_e32 v26, 64, v198
	v_max3_f32 v24, v24, v8, v9
	s_or_b64 vcc, s[0:1], s[34:35]
	v_xor_b32_e32 v25, 32, v198
	v_add_u32_e32 v26, 64, v26
	v_max3_f32 v24, v24, v10, v11
	v_cndmask_b32_e32 v15, v15, v200, vcc
	v_cmp_lt_i32_e32 vcc, v25, v26
	v_max3_f32 v24, v24, v12, v13
	v_max3_f32 v24, v24, v14, v15
	v_cndmask_b32_e32 v25, v198, v25, vcc
	v_lshlrev_b32_e32 v25, 2, v25
	ds_bpermute_b32 v26, v25, v24
	s_lshr_b32 s1, s39, 2
	s_mulk_i32 s1, 0x4080
	s_add_i32 s2, s1, 0x20400
	s_add_i32 s0, s44, s33
	s_waitcnt lgkmcnt(0)
	v_max_f32_e32 v26, v26, v26
	v_max_f32_e32 v24, v24, v26
	v_sub_f32_e32 v26, v64, v24
	v_mul_f32_e32 v26, 0x3fb8aa3b, v26
	v_sub_f32_e32 v28, v65, v24
	v_exp_f32_e32 v26, v26
	v_mul_f32_e32 v28, 0x3fb8aa3b, v28
	v_sub_f32_e32 v29, v66, v24
	v_exp_f32_e32 v28, v28
	v_mul_f32_e32 v29, 0x3fb8aa3b, v29
	v_sub_f32_e32 v30, v67, v24
	v_exp_f32_e32 v29, v29
	v_mul_f32_e32 v30, 0x3fb8aa3b, v30
	v_sub_f32_e32 v31, v68, v24
	v_exp_f32_e32 v30, v30
	v_mul_f32_e32 v31, 0x3fb8aa3b, v31
	v_sub_f32_e32 v44, v69, v24
	v_add_f32_e32 v27, 0, v26
	v_exp_f32_e32 v31, v31
	v_mul_f32_e32 v44, 0x3fb8aa3b, v44
	v_sub_f32_e32 v45, v70, v24
	v_add_f32_e32 v27, v28, v27
	v_exp_f32_e32 v44, v44
	v_mul_f32_e32 v45, 0x3fb8aa3b, v45
	v_sub_f32_e32 v46, v71, v24
	v_add_f32_e32 v27, v29, v27
	v_exp_f32_e32 v45, v45
	v_mul_f32_e32 v46, 0x3fb8aa3b, v46
	v_sub_f32_e32 v47, v72, v24
	v_add_f32_e32 v27, v30, v27
	v_exp_f32_e32 v46, v46
	v_mul_f32_e32 v47, 0x3fb8aa3b, v47
	v_sub_f32_e32 v63, v73, v24
	v_add_f32_e32 v27, v31, v27
	v_exp_f32_e32 v47, v47
	v_mul_f32_e32 v63, 0x3fb8aa3b, v63
	v_sub_f32_e32 v64, v74, v24
	v_add_f32_e32 v27, v44, v27
	v_exp_f32_e32 v63, v63
	v_mul_f32_e32 v64, 0x3fb8aa3b, v64
	v_sub_f32_e32 v65, v75, v24
	v_add_f32_e32 v27, v45, v27
	v_exp_f32_e32 v64, v64
	v_mul_f32_e32 v65, 0x3fb8aa3b, v65
	v_sub_f32_e32 v66, v76, v24
	v_add_f32_e32 v27, v46, v27
	v_exp_f32_e32 v65, v65
	v_mul_f32_e32 v66, 0x3fb8aa3b, v66
	v_sub_f32_e32 v67, v77, v24
	v_add_f32_e32 v27, v47, v27
	v_exp_f32_e32 v66, v66
	v_mul_f32_e32 v67, 0x3fb8aa3b, v67
	v_sub_f32_e32 v68, v85, v24
	v_add_f32_e32 v27, v63, v27
	v_exp_f32_e32 v67, v67
	v_mul_f32_e32 v68, 0x3fb8aa3b, v68
	v_sub_f32_e32 v69, v92, v24
	v_add_f32_e32 v27, v64, v27
	v_exp_f32_e32 v68, v68
	v_mul_f32_e32 v69, 0x3fb8aa3b, v69
	v_sub_f32_e32 v70, v93, v24
	v_add_f32_e32 v27, v65, v27
	v_exp_f32_e32 v69, v69
	v_mul_f32_e32 v70, 0x3fb8aa3b, v70
	v_sub_f32_e32 v71, v90, v24
	v_add_f32_e32 v27, v66, v27
	v_exp_f32_e32 v70, v70
	v_mul_f32_e32 v71, 0x3fb8aa3b, v71
	v_sub_f32_e32 v72, v91, v24
	v_add_f32_e32 v27, v67, v27
	v_exp_f32_e32 v71, v71
	v_mul_f32_e32 v72, 0x3fb8aa3b, v72
	v_sub_f32_e32 v73, v88, v24
	v_add_f32_e32 v27, v68, v27
	v_exp_f32_e32 v72, v72
	v_mul_f32_e32 v73, 0x3fb8aa3b, v73
	v_sub_f32_e32 v74, v89, v24
	v_add_f32_e32 v27, v69, v27
	v_exp_f32_e32 v73, v73
	v_mul_f32_e32 v74, 0x3fb8aa3b, v74
	v_sub_f32_e32 v75, v86, v24
	v_add_f32_e32 v27, v70, v27
	v_exp_f32_e32 v74, v74
	v_mul_f32_e32 v75, 0x3fb8aa3b, v75
	v_sub_f32_e32 v76, v87, v24
	v_add_f32_e32 v27, v71, v27
	v_exp_f32_e32 v75, v75
	v_mul_f32_e32 v76, 0x3fb8aa3b, v76
	v_sub_f32_e32 v77, v83, v24
	v_add_f32_e32 v27, v72, v27
	v_exp_f32_e32 v76, v76
	v_mul_f32_e32 v77, 0x3fb8aa3b, v77
	v_sub_f32_e32 v83, v84, v24
	v_add_f32_e32 v27, v73, v27
	v_exp_f32_e32 v77, v77
	v_mul_f32_e32 v83, 0x3fb8aa3b, v83
	v_sub_f32_e32 v81, v81, v24
	v_add_f32_e32 v27, v74, v27
	v_exp_f32_e32 v83, v83
	v_mul_f32_e32 v81, 0x3fb8aa3b, v81
	v_sub_f32_e32 v82, v82, v24
	v_add_f32_e32 v27, v75, v27
	v_exp_f32_e32 v81, v81
	v_mul_f32_e32 v82, 0x3fb8aa3b, v82
	v_sub_f32_e32 v78, v78, v24
	v_add_f32_e32 v27, v76, v27
	v_exp_f32_e32 v82, v82
	v_mul_f32_e32 v78, 0x3fb8aa3b, v78
	v_sub_f32_e32 v79, v79, v24
	v_add_f32_e32 v27, v77, v27
	v_exp_f32_e32 v78, v78
	v_mul_f32_e32 v79, 0x3fb8aa3b, v79
	v_sub_f32_e32 v61, v61, v24
	v_add_f32_e32 v27, v83, v27
	v_exp_f32_e32 v79, v79
	v_mul_f32_e32 v61, 0x3fb8aa3b, v61
	v_sub_f32_e32 v62, v62, v24
	v_add_f32_e32 v27, v81, v27
	v_exp_f32_e32 v61, v61
	v_mul_f32_e32 v62, 0x3fb8aa3b, v62
	v_sub_f32_e32 v59, v59, v24
	v_add_f32_e32 v27, v82, v27
	v_exp_f32_e32 v62, v62
	v_mul_f32_e32 v59, 0x3fb8aa3b, v59
	v_sub_f32_e32 v60, v60, v24
	v_add_f32_e32 v27, v78, v27
	v_exp_f32_e32 v59, v59
	v_mul_f32_e32 v60, 0x3fb8aa3b, v60
	v_sub_f32_e32 v57, v57, v24
	v_add_f32_e32 v27, v79, v27
	v_exp_f32_e32 v60, v60
	v_mul_f32_e32 v57, 0x3fb8aa3b, v57
	v_sub_f32_e32 v58, v58, v24
	v_add_f32_e32 v27, v61, v27
	v_exp_f32_e32 v57, v57
	v_mul_f32_e32 v58, 0x3fb8aa3b, v58
	v_sub_f32_e32 v55, v55, v24
	v_add_f32_e32 v27, v62, v27
	v_exp_f32_e32 v58, v58
	v_mul_f32_e32 v55, 0x3fb8aa3b, v55
	v_sub_f32_e32 v56, v56, v24
	v_add_f32_e32 v27, v59, v27
	v_exp_f32_e32 v55, v55
	v_mul_f32_e32 v56, 0x3fb8aa3b, v56
	v_sub_f32_e32 v53, v53, v24
	v_add_f32_e32 v27, v60, v27
	v_exp_f32_e32 v56, v56
	v_mul_f32_e32 v53, 0x3fb8aa3b, v53
	v_sub_f32_e32 v54, v54, v24
	v_add_f32_e32 v27, v57, v27
	v_exp_f32_e32 v53, v53
	v_mul_f32_e32 v54, 0x3fb8aa3b, v54
	v_sub_f32_e32 v52, v52, v24
	v_add_f32_e32 v27, v58, v27
	v_exp_f32_e32 v54, v54
	v_mul_f32_e32 v52, 0x3fb8aa3b, v52
	v_sub_f32_e32 v51, v51, v24
	v_add_f32_e32 v27, v55, v27
	v_exp_f32_e32 v52, v52
	v_mul_f32_e32 v51, 0x3fb8aa3b, v51
	v_sub_f32_e32 v50, v50, v24
	v_add_f32_e32 v27, v56, v27
	v_exp_f32_e32 v51, v51
	v_mul_f32_e32 v50, 0x3fb8aa3b, v50
	v_sub_f32_e32 v49, v49, v24
	v_add_f32_e32 v27, v53, v27
	v_exp_f32_e32 v50, v50
	v_mul_f32_e32 v49, 0x3fb8aa3b, v49
	v_sub_f32_e32 v48, v48, v24
	v_add_f32_e32 v27, v54, v27
	v_exp_f32_e32 v49, v49
	v_mul_f32_e32 v48, 0x3fb8aa3b, v48
	v_sub_f32_e32 v43, v43, v24
	v_add_f32_e32 v27, v52, v27
	v_exp_f32_e32 v48, v48
	v_mul_f32_e32 v43, 0x3fb8aa3b, v43
	v_sub_f32_e32 v42, v42, v24
	v_add_f32_e32 v27, v51, v27
	v_exp_f32_e32 v84, v43
	v_mul_f32_e32 v42, 0x3fb8aa3b, v42
	v_sub_f32_e32 v41, v41, v24
	v_add_f32_e32 v27, v50, v27
	v_exp_f32_e32 v85, v42
	v_mul_f32_e32 v41, 0x3fb8aa3b, v41
	v_sub_f32_e32 v40, v40, v24
	v_add_f32_e32 v27, v49, v27
	v_exp_f32_e32 v86, v41
	v_mul_f32_e32 v40, 0x3fb8aa3b, v40
	v_sub_f32_e32 v39, v39, v24
	v_add_f32_e32 v27, v48, v27
	v_exp_f32_e32 v87, v40
	v_mul_f32_e32 v39, 0x3fb8aa3b, v39
	v_sub_f32_e32 v38, v38, v24
	v_add_f32_e32 v27, v84, v27
	v_exp_f32_e32 v88, v39
	v_mul_f32_e32 v38, 0x3fb8aa3b, v38
	v_sub_f32_e32 v37, v37, v24
	v_add_f32_e32 v27, v85, v27
	v_exp_f32_e32 v89, v38
	v_mul_f32_e32 v37, 0x3fb8aa3b, v37
	v_sub_f32_e32 v36, v36, v24
	v_sub_f32_e32 v1, v1, v24
	v_add_f32_e32 v27, v86, v27
	v_exp_f32_e32 v90, v37
	v_mul_f32_e32 v36, 0x3fb8aa3b, v36
	v_sub_f32_e32 v35, v35, v24
	v_mul_f32_e32 v1, 0x3fb8aa3b, v1
	v_add_f32_e32 v27, v87, v27
	v_exp_f32_e32 v91, v36
	v_mul_f32_e32 v35, 0x3fb8aa3b, v35
	v_sub_f32_e32 v34, v34, v24
	v_exp_f32_e32 v142, v1
	v_sub_f32_e32 v1, v2, v24
	v_add_f32_e32 v27, v88, v27
	v_exp_f32_e32 v35, v35
	v_mul_f32_e32 v34, 0x3fb8aa3b, v34
	v_sub_f32_e32 v33, v33, v24
	v_mul_f32_e32 v1, 0x3fb8aa3b, v1
	v_add_f32_e32 v27, v89, v27
	v_exp_f32_e32 v92, v34
	v_mul_f32_e32 v33, 0x3fb8aa3b, v33
	v_sub_f32_e32 v32, v32, v24
	v_exp_f32_e32 v143, v1
	v_sub_f32_e32 v1, v3, v24
	v_add_f32_e32 v27, v90, v27
	v_exp_f32_e32 v33, v33
	v_mul_f32_e32 v32, 0x3fb8aa3b, v32
	v_sub_f32_e32 v23, v23, v24
	v_mul_f32_e32 v1, 0x3fb8aa3b, v1
	v_add_f32_e32 v27, v91, v27
	v_exp_f32_e32 v32, v32
	v_mul_f32_e32 v23, 0x3fb8aa3b, v23
	v_sub_f32_e32 v22, v22, v24
	v_exp_f32_e32 v144, v1
	v_sub_f32_e32 v1, v4, v24
	v_add_f32_e32 v27, v35, v27
	v_exp_f32_e32 v93, v23
	v_mul_f32_e32 v22, 0x3fb8aa3b, v22
	v_sub_f32_e32 v21, v21, v24
	v_mul_f32_e32 v1, 0x3fb8aa3b, v1
	v_add_f32_e32 v27, v92, v27
	v_exp_f32_e32 v94, v22
	v_mul_f32_e32 v21, 0x3fb8aa3b, v21
	v_sub_f32_e32 v20, v20, v24
	v_exp_f32_e32 v145, v1
	v_sub_f32_e32 v1, v5, v24
	v_add_f32_e32 v27, v33, v27
	v_exp_f32_e32 v95, v21
	v_mul_f32_e32 v20, 0x3fb8aa3b, v20
	v_sub_f32_e32 v19, v19, v24
	v_mul_f32_e32 v1, 0x3fb8aa3b, v1
	v_add_f32_e32 v27, v32, v27
	v_exp_f32_e32 v96, v20
	v_mul_f32_e32 v19, 0x3fb8aa3b, v19
	v_sub_f32_e32 v18, v18, v24
	v_exp_f32_e32 v146, v1
	v_sub_f32_e32 v1, v6, v24
	v_add_f32_e32 v23, v93, v27
	v_exp_f32_e32 v137, v19
	v_mul_f32_e32 v18, 0x3fb8aa3b, v18
	v_sub_f32_e32 v17, v17, v24
	v_mul_f32_e32 v1, 0x3fb8aa3b, v1
	v_add_f32_e32 v22, v94, v23
	v_exp_f32_e32 v138, v18
	v_mul_f32_e32 v17, 0x3fb8aa3b, v17
	v_sub_f32_e32 v16, v16, v24
	v_exp_f32_e32 v147, v1
	v_sub_f32_e32 v1, v7, v24
	v_add_f32_e32 v21, v95, v22
	v_exp_f32_e32 v139, v17
	v_mul_f32_e32 v16, 0x3fb8aa3b, v16
	v_sub_f32_e32 v0, v0, v24
	v_mul_f32_e32 v1, 0x3fb8aa3b, v1
	v_add_f32_e32 v20, v96, v21
	v_exp_f32_e32 v140, v16
	v_mul_f32_e32 v0, 0x3fb8aa3b, v0
	v_exp_f32_e32 v148, v1
	v_sub_f32_e32 v1, v8, v24
	v_add_f32_e32 v19, v137, v20
	v_exp_f32_e32 v141, v0
	v_mul_f32_e32 v1, 0x3fb8aa3b, v1
	v_add_f32_e32 v18, v138, v19
	v_exp_f32_e32 v149, v1
	v_sub_f32_e32 v1, v9, v24
	v_add_f32_e32 v17, v139, v18
	v_mul_f32_e32 v1, 0x3fb8aa3b, v1
	v_add_f32_e32 v16, v140, v17
	v_exp_f32_e32 v150, v1
	v_sub_f32_e32 v1, v10, v24
	v_add_f32_e32 v0, v141, v16
	v_mul_f32_e32 v1, 0x3fb8aa3b, v1
	v_add_f32_e32 v0, v142, v0
	v_exp_f32_e32 v151, v1
	v_sub_f32_e32 v1, v11, v24
	v_add_f32_e32 v0, v143, v0
	v_mul_f32_e32 v1, 0x3fb8aa3b, v1
	v_add_f32_e32 v0, v144, v0
	v_exp_f32_e32 v152, v1
	v_sub_f32_e32 v1, v12, v24
	v_add_f32_e32 v0, v145, v0
	v_mul_f32_e32 v1, 0x3fb8aa3b, v1
	v_add_f32_e32 v0, v146, v0
	v_exp_f32_e32 v153, v1
	v_sub_f32_e32 v1, v13, v24
	v_add_f32_e32 v0, v147, v0
	v_mul_f32_e32 v1, 0x3fb8aa3b, v1
	v_add_f32_e32 v0, v148, v0
	v_exp_f32_e32 v154, v1
	v_sub_f32_e32 v1, v14, v24
	v_add_f32_e32 v0, v149, v0
	v_mul_f32_e32 v1, 0x3fb8aa3b, v1
	v_add_f32_e32 v0, v150, v0
	v_exp_f32_e32 v155, v1
	v_sub_f32_e32 v1, v15, v24
	v_add_f32_e32 v0, v151, v0
	v_mul_f32_e32 v1, 0x3fb8aa3b, v1
	v_add_f32_e32 v0, v152, v0
	v_exp_f32_e32 v156, v1
	v_add_f32_e32 v0, v153, v0
	v_add_f32_e32 v0, v154, v0
	v_add_f32_e32 v0, v155, v0
	v_add_f32_e32 v0, v156, v0
	ds_bpermute_b32 v1, v25, v0
	v_cvt_pk_bf16_f32 v2, v31, v44
	v_add_u32_e32 v44, 0x9000, v136
	ds_read2_b64 v[4:7], v44 offset1:2
	ds_read2_b64 v[36:39], v44 offset0:4 offset1:6
	v_cvt_pk_bf16_f32 v3, v45, v46
	s_waitcnt lgkmcnt(2)
	v_add_f32_e32 v0, v0, v1
	v_sub_f32_e32 v1, v80, v24
	v_mul_f32_e32 v1, 0x3fb8aa3b, v1
	v_exp_f32_e32 v1, v1
	v_add_u32_e32 v45, 0xd000, v136
	v_cvt_pk_bf16_f32 v40, v47, v63
	v_cvt_pk_bf16_f32 v41, v64, v65
	v_add_f32_e32 v34, v1, v0
	v_cvt_pk_bf16_f32 v0, v26, v28
	v_cvt_pk_bf16_f32 v1, v29, v30
	v_cvt_pk_bf16_f32 v42, v66, v67
	v_cvt_pk_bf16_f32 v43, v68, v69
	s_waitcnt lgkmcnt(1)
	v_mfma_f32_32x32x16_bf16 v[16:31], v[4:7], v[0:3], 0
	ds_read2_b64 v[4:7], v45 offset0:96 offset1:98
	s_and_b32 s0, s0, 0xc0
	s_mov_b64 vcc, s[46:47]
	v_readlane_b32 s1, v254, 36
	s_add_i32 s33, s33, 64
	v_rcp_f32_e32 v34, v34
	s_waitcnt lgkmcnt(1)
	v_mfma_f32_32x32x16_bf16 v[16:31], v[36:39], v[40:43], v[16:31]
	ds_read2_b64 v[36:39], v45 offset0:100 offset1:102
	s_waitcnt lgkmcnt(1)
	v_mfma_f32_32x32x16_bf16 v[0:15], v[4:7], v[0:3], 0
	s_waitcnt lgkmcnt(0)
	v_mfma_f32_32x32x16_bf16 v[0:15], v[36:39], v[40:43], v[0:15]
	ds_read2_b64 v[40:43], v44 offset0:8 offset1:10
	v_cvt_pk_bf16_f32 v36, v70, v71
	v_cvt_pk_bf16_f32 v37, v72, v73
	v_cvt_pk_bf16_f32 v38, v74, v75
	v_cvt_pk_bf16_f32 v39, v76, v77
	s_waitcnt lgkmcnt(0)
	s_nop 0
	v_mfma_f32_32x32x16_bf16 v[16:31], v[40:43], v[36:39], v[16:31]
	ds_read2_b64 v[40:43], v45 offset0:104 offset1:106
	s_waitcnt lgkmcnt(0)
	v_mfma_f32_32x32x16_bf16 v[0:15], v[40:43], v[36:39], v[0:15]
	ds_read2_b64 v[40:43], v44 offset0:12 offset1:14
	v_cvt_pk_bf16_f32 v36, v83, v81
	v_cvt_pk_bf16_f32 v37, v82, v78
	v_cvt_pk_bf16_f32 v38, v79, v61
	v_cvt_pk_bf16_f32 v39, v62, v59
	s_waitcnt lgkmcnt(0)
	s_nop 0
	v_mfma_f32_32x32x16_bf16 v[16:31], v[40:43], v[36:39], v[16:31]
	ds_read2_b64 v[40:43], v45 offset0:108 offset1:110
	s_waitcnt lgkmcnt(0)
	v_mfma_f32_32x32x16_bf16 v[0:15], v[40:43], v[36:39], v[0:15]
	ds_read2_b64 v[40:43], v44 offset0:16 offset1:18
	v_cvt_pk_bf16_f32 v36, v60, v57
	v_cvt_pk_bf16_f32 v37, v58, v55
	v_cvt_pk_bf16_f32 v38, v56, v53
	v_cvt_pk_bf16_f32 v39, v54, v52
	s_waitcnt lgkmcnt(0)
	s_nop 0
	v_mfma_f32_32x32x16_bf16 v[16:31], v[40:43], v[36:39], v[16:31]
	ds_read2_b64 v[40:43], v45 offset0:112 offset1:114
	s_waitcnt lgkmcnt(0)
	v_mfma_f32_32x32x16_bf16 v[0:15], v[40:43], v[36:39], v[0:15]
	ds_read2_b64 v[40:43], v44 offset0:20 offset1:22
	v_cvt_pk_bf16_f32 v36, v51, v50
	v_cvt_pk_bf16_f32 v37, v49, v48
	v_cvt_pk_bf16_f32 v38, v84, v85
	v_cvt_pk_bf16_f32 v39, v86, v87
	s_waitcnt lgkmcnt(0)
	s_nop 0
	v_mfma_f32_32x32x16_bf16 v[16:31], v[40:43], v[36:39], v[16:31]
	ds_read2_b64 v[40:43], v45 offset0:116 offset1:118
	s_waitcnt lgkmcnt(0)
	v_mfma_f32_32x32x16_bf16 v[0:15], v[40:43], v[36:39], v[0:15]
	ds_read2_b64 v[40:43], v44 offset0:24 offset1:26
	v_cvt_pk_bf16_f32 v36, v88, v89
	v_cvt_pk_bf16_f32 v37, v90, v91
	v_cvt_pk_bf16_f32 v38, v35, v92
	v_cvt_pk_bf16_f32 v39, v33, v32
	v_lshl_add_u64 v[32:33], s[2:3], 0, v[98:99]
	v_lshlrev_b64 v[32:33], 9, v[32:33]
	s_waitcnt lgkmcnt(0)
	v_mfma_f32_32x32x16_bf16 v[16:31], v[40:43], v[36:39], v[16:31]
	ds_read2_b64 v[40:43], v45 offset0:120 offset1:122
	v_lshl_add_u64 v[32:33], vcc, 0, v[32:33]
	s_lshl_b32 s2, s0, 1
	v_lshl_add_u64 v[32:33], v[32:33], 0, s[2:3]
	s_and_b32 s0, s38, 4
	s_or_b32 s0, s0, s1
	s_lshr_b32 s0, s0, 2
	s_waitcnt lgkmcnt(0)
	v_mfma_f32_32x32x16_bf16 v[0:15], v[40:43], v[36:39], v[0:15]
	ds_read2_b64 v[40:43], v44 offset0:28 offset1:30
	v_cvt_pk_bf16_f32 v36, v93, v94
	v_cvt_pk_bf16_f32 v37, v95, v96
	v_cvt_pk_bf16_f32 v38, v137, v138
	v_cvt_pk_bf16_f32 v39, v139, v140
	v_lshlrev_b32_e32 v96, 1, v100
	v_lshl_add_u64 v[32:33], v[32:33], 0, v[96:97]
	s_waitcnt lgkmcnt(0)
	v_mfma_f32_32x32x16_bf16 v[16:31], v[40:43], v[36:39], v[16:31]
	ds_read2_b64 v[40:43], v45 offset0:124 offset1:126
	s_mul_i32 s2, s0, 0x4080
	v_lshl_add_u64 v[50:51], s[2:3], 0, v[98:99]
	s_and_b32 s0, s33, 0xc0
	v_or_b32_e32 v35, s0, v134
	v_lshlrev_b64 v[50:51], 9, v[50:51]
	v_lshl_add_u64 v[50:51], vcc, 0, v[50:51]
	s_waitcnt lgkmcnt(0)
	v_mfma_f32_32x32x16_bf16 v[0:15], v[40:43], v[36:39], v[0:15]
	ds_read2_b64 v[40:43], v44 offset0:32 offset1:34
	v_cvt_pk_bf16_f32 v36, v141, v142
	v_cvt_pk_bf16_f32 v37, v143, v144
	v_cvt_pk_bf16_f32 v38, v145, v146
	v_cvt_pk_bf16_f32 v39, v147, v148
	v_lshlrev_b32_e32 v96, 1, v35
	v_lshl_add_u64 v[50:51], v[50:51], 0, v[96:97]
	s_waitcnt lgkmcnt(0)
	v_mfma_f32_32x32x16_bf16 v[16:31], v[40:43], v[36:39], v[16:31]
	ds_read2_b64 v[40:43], v45 offset0:128 offset1:130
	s_add_u32 s36, s36, 4
	s_addc_u32 s37, s37, 0
	s_mov_b64 s[0:1], 0x80
	s_cmp_eq_u32 s38, 8
	s_waitcnt lgkmcnt(0)
	v_mfma_f32_32x32x16_bf16 v[0:15], v[40:43], v[36:39], v[0:15]
	ds_read2_b64 v[40:43], v44 offset0:36 offset1:38
	v_cvt_pk_bf16_f32 v36, v149, v150
	v_cvt_pk_bf16_f32 v37, v151, v152
	v_cvt_pk_bf16_f32 v38, v153, v154
	v_cvt_pk_bf16_f32 v39, v155, v156
	s_waitcnt lgkmcnt(0)
	s_nop 0
	v_mfma_f32_32x32x16_bf16 v[16:31], v[40:43], v[36:39], v[16:31]
	ds_read2_b64 v[40:43], v45 offset0:132 offset1:134
	s_waitcnt lgkmcnt(0)
	v_mfma_f32_32x32x16_bf16 v[0:15], v[40:43], v[36:39], v[0:15]
	global_load_dwordx2 v[48:49], v[32:33], off
	global_load_dwordx2 v[46:47], v[32:33], off offset:16
	global_load_dwordx2 v[44:45], v[32:33], off offset:32
	global_load_dwordx2 v[42:43], v[32:33], off offset:48
	global_load_dwordx2 v[40:41], v[32:33], off offset:64
	global_load_dwordx2 v[38:39], v[32:33], off offset:80
	global_load_dwordx2 v[36:37], v[32:33], off offset:96
	s_nop 0
	global_load_dwordx2 v[32:33], v[32:33], off offset:112
	s_nop 0
	global_load_dwordx4 v[80:83], v[50:51], off
	global_load_dwordx4 v[84:87], v[50:51], off offset:32
	global_load_dwordx4 v[88:91], v[50:51], off offset:64
	global_load_dwordx4 v[92:95], v[50:51], off offset:96
	v_pk_mul_f32 v[16:17], v[16:17], v[34:35] op_sel_hi:[1,0]
	v_pk_mul_f32 v[18:19], v[18:19], v[34:35] op_sel_hi:[1,0]
	v_pk_mul_f32 v[0:1], v[0:1], v[34:35] op_sel_hi:[1,0]
	v_pk_mul_f32 v[2:3], v[2:3], v[34:35] op_sel_hi:[1,0]
	s_waitcnt vmcnt(11)
	v_lshlrev_b32_e32 v50, 16, v48
	v_and_b32_e32 v51, 0xffff0000, v48
	v_lshlrev_b32_e32 v48, 16, v49
	v_and_b32_e32 v49, 0xffff0000, v49
	v_pk_mul_f32 v[16:17], v[16:17], v[50:51]
	v_pk_mul_f32 v[18:19], v[18:19], v[48:49]
	v_cvt_pk_bf16_f32 v16, v16, v17
	v_cvt_pk_bf16_f32 v17, v18, v19
	global_store_dwordx2 v[102:103], v[16:17], off offset:-64
	v_pk_mul_f32 v[16:17], v[20:21], v[34:35] op_sel_hi:[1,0]
	s_waitcnt vmcnt(11)
	v_lshlrev_b32_e32 v18, 16, v46
	v_and_b32_e32 v19, 0xffff0000, v46
	v_pk_mul_f32 v[16:17], v[16:17], v[18:19]
	v_pk_mul_f32 v[18:19], v[22:23], v[34:35] op_sel_hi:[1,0]
	v_lshlrev_b32_e32 v20, 16, v47
	v_and_b32_e32 v21, 0xffff0000, v47
	v_pk_mul_f32 v[18:19], v[18:19], v[20:21]
	v_cvt_pk_bf16_f32 v16, v16, v17
	v_cvt_pk_bf16_f32 v17, v18, v19
	global_store_dwordx2 v[102:103], v[16:17], off offset:-48
	v_pk_mul_f32 v[16:17], v[24:25], v[34:35] op_sel_hi:[1,0]
	s_waitcnt vmcnt(11)
	v_lshlrev_b32_e32 v18, 16, v44
	v_and_b32_e32 v19, 0xffff0000, v44
	v_pk_mul_f32 v[16:17], v[16:17], v[18:19]
	v_pk_mul_f32 v[18:19], v[26:27], v[34:35] op_sel_hi:[1,0]
	v_lshlrev_b32_e32 v20, 16, v45
	v_and_b32_e32 v21, 0xffff0000, v45
	v_pk_mul_f32 v[18:19], v[18:19], v[20:21]
	v_cvt_pk_bf16_f32 v16, v16, v17
	v_cvt_pk_bf16_f32 v17, v18, v19
	global_store_dwordx2 v[102:103], v[16:17], off offset:-32
	v_pk_mul_f32 v[16:17], v[28:29], v[34:35] op_sel_hi:[1,0]
	s_waitcnt vmcnt(11)
	v_lshlrev_b32_e32 v18, 16, v42
	v_and_b32_e32 v19, 0xffff0000, v42
	v_pk_mul_f32 v[16:17], v[16:17], v[18:19]
	v_pk_mul_f32 v[18:19], v[30:31], v[34:35] op_sel_hi:[1,0]
	v_lshlrev_b32_e32 v20, 16, v43
	v_and_b32_e32 v21, 0xffff0000, v43
	v_pk_mul_f32 v[18:19], v[18:19], v[20:21]
	v_cvt_pk_bf16_f32 v16, v16, v17
	v_cvt_pk_bf16_f32 v17, v18, v19
	global_store_dwordx2 v[102:103], v[16:17], off offset:-16
	s_waitcnt vmcnt(11)
	v_lshlrev_b32_e32 v16, 16, v40
	v_and_b32_e32 v17, 0xffff0000, v40
	v_pk_mul_f32 v[0:1], v[0:1], v[16:17]
	v_lshlrev_b32_e32 v16, 16, v41
	v_and_b32_e32 v17, 0xffff0000, v41
	v_pk_mul_f32 v[2:3], v[2:3], v[16:17]
	v_cvt_pk_bf16_f32 v0, v0, v1
	v_cvt_pk_bf16_f32 v1, v2, v3
	global_store_dwordx2 v[102:103], v[0:1], off
	v_pk_mul_f32 v[0:1], v[4:5], v[34:35] op_sel_hi:[1,0]
	s_waitcnt vmcnt(11)
	v_lshlrev_b32_e32 v2, 16, v38
	v_and_b32_e32 v3, 0xffff0000, v38
	v_pk_mul_f32 v[0:1], v[0:1], v[2:3]
	v_pk_mul_f32 v[2:3], v[6:7], v[34:35] op_sel_hi:[1,0]
	v_lshlrev_b32_e32 v4, 16, v39
	v_and_b32_e32 v5, 0xffff0000, v39
	v_pk_mul_f32 v[2:3], v[2:3], v[4:5]
	v_cvt_pk_bf16_f32 v0, v0, v1
	v_cvt_pk_bf16_f32 v1, v2, v3
	global_store_dwordx2 v[102:103], v[0:1], off offset:16
	v_pk_mul_f32 v[0:1], v[8:9], v[34:35] op_sel_hi:[1,0]
	s_waitcnt vmcnt(11)
	v_lshlrev_b32_e32 v2, 16, v36
	v_and_b32_e32 v3, 0xffff0000, v36
	v_pk_mul_f32 v[0:1], v[0:1], v[2:3]
	v_pk_mul_f32 v[2:3], v[10:11], v[34:35] op_sel_hi:[1,0]
	v_lshlrev_b32_e32 v4, 16, v37
	v_and_b32_e32 v5, 0xffff0000, v37
	v_pk_mul_f32 v[2:3], v[2:3], v[4:5]
	v_cvt_pk_bf16_f32 v0, v0, v1
	v_cvt_pk_bf16_f32 v1, v2, v3
	global_store_dwordx2 v[102:103], v[0:1], off offset:32
	v_pk_mul_f32 v[0:1], v[12:13], v[34:35] op_sel_hi:[1,0]
	s_waitcnt vmcnt(11)
	v_lshlrev_b32_e32 v2, 16, v32
	v_and_b32_e32 v3, 0xffff0000, v32
	v_pk_mul_f32 v[0:1], v[0:1], v[2:3]
	v_pk_mul_f32 v[2:3], v[14:15], v[34:35] op_sel_hi:[1,0]
	v_lshlrev_b32_e32 v4, 16, v33
	v_and_b32_e32 v5, 0xffff0000, v33
	v_pk_mul_f32 v[2:3], v[2:3], v[4:5]
	v_cvt_pk_bf16_f32 v0, v0, v1
	v_cvt_pk_bf16_f32 v1, v2, v3
	global_store_dwordx2 v[102:103], v[0:1], off offset:48
	v_lshl_add_u64 v[102:103], v[102:103], 0, s[0:1]
	s_cbranch_scc0 .LBB0_2056
	v_readlane_b32 s91, v254, 17
	v_readlane_b32 s24, v254, 52
	s_mov_b32 s37, s3
	s_movk_i32 s25, 0x90
	s_branch .LBB0_1999
